# de-serialised dependent load chains hipcc emitted in ret/gmlp/pool/conv staging (issue loads together, wait once); bias_task + xg loop hand-written
# speedup vs baseline: 1.0361x; 1.0201x over previous
.LBB0_92:
	v_readlane_b32 s40, v254, 5
	v_readlane_b32 s41, v254, 6
	v_readlane_b32 s42, v254, 7
	v_readlane_b32 s43, v254, 8
	v_readlane_b32 s54, v255, 7
	v_readlane_b32 s55, v255, 8
	v_add_u32_e32 v2, 0xfffff580, v144
	v_cmp_gt_i32_e32 vcc, s93, v2
	v_add_u32_e32 v11, 0xffffe580, v144
	s_nop 1
	v_cndmask_b32_e32 v14, v11, v2, vcc
	v_mov_b32_e32 v15, 0
	v_mov_b32_e32 v11, s43
	v_mov_b32_e32 v16, s41
	v_cndmask_b32_e32 v17, v11, v16, vcc
	v_mov_b32_e32 v11, s42
	v_mov_b32_e32 v16, s40
	v_cndmask_b32_e32 v16, v11, v16, vcc
	v_cndmask_b32_e64 v13, v1, 0, vcc
	v_cndmask_b32_e64 v12, v0, 0, vcc
	v_lshlrev_b64 v[14:15], 12, v[14:15]
	v_lshl_add_u64 v[12:13], s[54:55], 0, v[12:13]
	s_mov_b64 s[2:3], 0x1000
	v_lshl_add_u64 v[14:15], v[16:17], 0, v[14:15]
	v_lshl_add_u64 v[56:57], v[12:13], 0, s[2:3]
	v_lshl_add_u64 v[40:41], v[14:15], 0, v[200:201]
	v_lshl_add_u64 v[42:43], v[40:41], 0, s[2:3]
	v_lshl_add_u64 v[44:45], v[42:43], 0, s[2:3]
	v_lshl_add_u64 v[46:47], v[44:45], 0, s[2:3]
	v_mov_b32_e32 v135, v201
	v_mov_b32_e32 v137, v201
	v_mov_b32_e32 v139, v201
	v_lshl_add_u64 v[48:49], v[56:57], 0, v[200:201]
	v_lshl_add_u64 v[50:51], v[56:57], 0, v[134:135]
	v_lshl_add_u64 v[52:53], v[56:57], 0, v[136:137]
	v_lshl_add_u64 v[54:55], v[56:57], 0, v[138:139]
	global_load_dwordx4 v[20:23], v[128:129], off
	global_load_dwordx4 v[24:27], v[128:129], off offset:1024
	global_load_dwordx4 v[28:31], v[128:129], off offset:2048
	global_load_dwordx4 v[32:35], v[128:129], off offset:3072
	global_load_dwordx4 v[146:149], v[48:49], off
	global_load_dwordx4 v[150:153], v[50:51], off
	global_load_dwordx4 v[154:157], v[52:53], off
	global_load_dwordx4 v[158:161], v[54:55], off
	global_load_dwordx4 v[64:67], v[40:41], off
	global_load_dwordx4 v[68:71], v[40:41], off offset:1024
	global_load_dwordx4 v[72:75], v[40:41], off offset:2048
	global_load_dwordx4 v[76:79], v[40:41], off offset:3072
	global_load_dwordx4 v[80:83], v[42:43], off
	global_load_dwordx4 v[84:87], v[42:43], off offset:1024
	global_load_dwordx4 v[88:91], v[42:43], off offset:2048
	global_load_dwordx4 v[92:95], v[42:43], off offset:3072
	global_load_dwordx4 v[96:99], v[44:45], off
	global_load_dwordx4 v[100:103], v[44:45], off offset:1024
	global_load_dwordx4 v[104:107], v[44:45], off offset:2048
	global_load_dwordx4 v[108:111], v[44:45], off offset:3072
	global_load_dwordx4 v[112:115], v[46:47], off
	global_load_dwordx4 v[116:119], v[46:47], off offset:1024
	global_load_dwordx4 v[120:123], v[46:47], off offset:2048
	global_load_dwordx4 v[124:127], v[46:47], off offset:3072
	v_ashrrev_i32_e32 v3, 31, v2
	v_lshlrev_b64 v[60:61], 11, v[2:3]
	v_lshl_add_u64 v[60:61], v[132:133], 0, v[60:61]
	v_lshl_add_u64 v[58:59], v[60:61], 0, s[2:3]
	v_lshlrev_b64 v[62:63], 7, v[2:3]
	v_lshl_add_u64 v[62:63], v[130:131], 0, v[62:63]
	s_waitcnt vmcnt(16)
	v_pk_add_f32 v[146:147], v[146:147], 1.0 op_sel_hi:[1,0]
	v_pk_add_f32 v[148:149], v[148:149], 1.0 op_sel_hi:[1,0]
	v_pk_add_f32 v[150:151], v[150:151], 1.0 op_sel_hi:[1,0]
	v_pk_add_f32 v[152:153], v[152:153], 1.0 op_sel_hi:[1,0]
	v_pk_add_f32 v[154:155], v[154:155], 1.0 op_sel_hi:[1,0]
	v_pk_add_f32 v[156:157], v[156:157], 1.0 op_sel_hi:[1,0]
	v_pk_add_f32 v[158:159], v[158:159], 1.0 op_sel_hi:[1,0]
	v_pk_add_f32 v[160:161], v[160:161], 1.0 op_sel_hi:[1,0]
	s_waitcnt vmcnt(12)
	v_mul_f32_e32 v36, v65, v65
	v_fmac_f32_e32 v36, v64, v64
	v_fmac_f32_e32 v36, v66, v66
	v_fmac_f32_e32 v36, v67, v67
	v_mul_f32_e32 v37, v69, v69
	v_fmac_f32_e32 v37, v68, v68
	v_fmac_f32_e32 v37, v70, v70
	v_fmac_f32_e32 v37, v71, v71
	v_mul_f32_e32 v38, v73, v73
	v_fmac_f32_e32 v38, v72, v72
	v_fmac_f32_e32 v38, v74, v74
	v_fmac_f32_e32 v38, v75, v75
	v_mul_f32_e32 v39, v77, v77
	v_fmac_f32_e32 v39, v76, v76
	v_fmac_f32_e32 v39, v78, v78
	v_fmac_f32_e32 v39, v79, v79
	v_add_f32_e32 v162, v36, v37
	v_add_f32_e32 v162, v162, v38
	v_add_f32_e32 v162, v162, v39
	v_pk_mul_f32 v[64:65], v[64:65], v[20:21]
	v_pk_mul_f32 v[66:67], v[66:67], v[22:23]
	v_pk_mul_f32 v[64:65], v[64:65], v[146:147]
	v_pk_mul_f32 v[66:67], v[66:67], v[148:149]
	v_cvt_pk_bf16_f32 v64, v64, v65
	v_cvt_pk_bf16_f32 v65, v66, v67
	v_pk_mul_f32 v[68:69], v[68:69], v[24:25]
	v_pk_mul_f32 v[70:71], v[70:71], v[26:27]
	v_pk_mul_f32 v[68:69], v[68:69], v[150:151]
	v_pk_mul_f32 v[70:71], v[70:71], v[152:153]
	v_cvt_pk_bf16_f32 v68, v68, v69
	v_cvt_pk_bf16_f32 v69, v70, v71
	v_pk_mul_f32 v[72:73], v[72:73], v[28:29]
	v_pk_mul_f32 v[74:75], v[74:75], v[30:31]
	v_pk_mul_f32 v[72:73], v[72:73], v[154:155]
	v_pk_mul_f32 v[74:75], v[74:75], v[156:157]
	v_cvt_pk_bf16_f32 v72, v72, v73
	v_cvt_pk_bf16_f32 v73, v74, v75
	v_pk_mul_f32 v[76:77], v[76:77], v[32:33]
	v_pk_mul_f32 v[78:79], v[78:79], v[34:35]
	v_pk_mul_f32 v[76:77], v[76:77], v[158:159]
	v_pk_mul_f32 v[78:79], v[78:79], v[160:161]
	v_cvt_pk_bf16_f32 v76, v76, v77
	v_cvt_pk_bf16_f32 v77, v78, v79
	global_store_dwordx2 v[60:61], v[64:65], off
	global_store_dwordx2 v[60:61], v[68:69], off offset:512
	global_store_dwordx2 v[60:61], v[72:73], off offset:1024
	global_store_dwordx2 v[60:61], v[76:77], off offset:1536
	s_waitcnt vmcnt(12)
	v_mul_f32_e32 v36, v81, v81
	v_fmac_f32_e32 v36, v80, v80
	v_fmac_f32_e32 v36, v82, v82
	v_fmac_f32_e32 v36, v83, v83
	v_mul_f32_e32 v37, v85, v85
	v_fmac_f32_e32 v37, v84, v84
	v_fmac_f32_e32 v37, v86, v86
	v_fmac_f32_e32 v37, v87, v87
	v_mul_f32_e32 v38, v89, v89
	v_fmac_f32_e32 v38, v88, v88
	v_fmac_f32_e32 v38, v90, v90
	v_fmac_f32_e32 v38, v91, v91
	v_mul_f32_e32 v39, v93, v93
	v_fmac_f32_e32 v39, v92, v92
	v_fmac_f32_e32 v39, v94, v94
	v_fmac_f32_e32 v39, v95, v95
	v_add_f32_e32 v163, v36, v37
	v_add_f32_e32 v163, v163, v38
	v_add_f32_e32 v163, v163, v39
	v_pk_mul_f32 v[80:81], v[80:81], v[20:21]
	v_pk_mul_f32 v[82:83], v[82:83], v[22:23]
	v_pk_mul_f32 v[80:81], v[80:81], v[146:147]
	v_pk_mul_f32 v[82:83], v[82:83], v[148:149]
	v_cvt_pk_bf16_f32 v80, v80, v81
	v_cvt_pk_bf16_f32 v81, v82, v83
	v_pk_mul_f32 v[84:85], v[84:85], v[24:25]
	v_pk_mul_f32 v[86:87], v[86:87], v[26:27]
	v_pk_mul_f32 v[84:85], v[84:85], v[150:151]
	v_pk_mul_f32 v[86:87], v[86:87], v[152:153]
	v_cvt_pk_bf16_f32 v84, v84, v85
	v_cvt_pk_bf16_f32 v85, v86, v87
	v_pk_mul_f32 v[88:89], v[88:89], v[28:29]
	v_pk_mul_f32 v[90:91], v[90:91], v[30:31]
	v_pk_mul_f32 v[88:89], v[88:89], v[154:155]
	v_pk_mul_f32 v[90:91], v[90:91], v[156:157]
	v_cvt_pk_bf16_f32 v88, v88, v89
	v_cvt_pk_bf16_f32 v89, v90, v91
	v_pk_mul_f32 v[92:93], v[92:93], v[32:33]
	v_pk_mul_f32 v[94:95], v[94:95], v[34:35]
	v_pk_mul_f32 v[92:93], v[92:93], v[158:159]
	v_pk_mul_f32 v[94:95], v[94:95], v[160:161]
	v_cvt_pk_bf16_f32 v92, v92, v93
	v_cvt_pk_bf16_f32 v93, v94, v95
	global_store_dwordx2 v[60:61], v[80:81], off offset:2048
	global_store_dwordx2 v[60:61], v[84:85], off offset:2560
	global_store_dwordx2 v[60:61], v[88:89], off offset:3072
	global_store_dwordx2 v[60:61], v[92:93], off offset:3584
	s_waitcnt vmcnt(12)
	v_mul_f32_e32 v36, v97, v97
	v_fmac_f32_e32 v36, v96, v96
	v_fmac_f32_e32 v36, v98, v98
	v_fmac_f32_e32 v36, v99, v99
	v_mul_f32_e32 v37, v101, v101
	v_fmac_f32_e32 v37, v100, v100
	v_fmac_f32_e32 v37, v102, v102
	v_fmac_f32_e32 v37, v103, v103
	v_mul_f32_e32 v38, v105, v105
	v_fmac_f32_e32 v38, v104, v104
	v_fmac_f32_e32 v38, v106, v106
	v_fmac_f32_e32 v38, v107, v107
	v_mul_f32_e32 v39, v109, v109
	v_fmac_f32_e32 v39, v108, v108
	v_fmac_f32_e32 v39, v110, v110
	v_fmac_f32_e32 v39, v111, v111
	v_add_f32_e32 v164, v36, v37
	v_add_f32_e32 v164, v164, v38
	v_add_f32_e32 v164, v164, v39
	v_pk_mul_f32 v[96:97], v[96:97], v[20:21]
	v_pk_mul_f32 v[98:99], v[98:99], v[22:23]
	v_pk_mul_f32 v[96:97], v[96:97], v[146:147]
	v_pk_mul_f32 v[98:99], v[98:99], v[148:149]
	v_cvt_pk_bf16_f32 v96, v96, v97
	v_cvt_pk_bf16_f32 v97, v98, v99
	v_pk_mul_f32 v[100:101], v[100:101], v[24:25]
	v_pk_mul_f32 v[102:103], v[102:103], v[26:27]
	v_pk_mul_f32 v[100:101], v[100:101], v[150:151]
	v_pk_mul_f32 v[102:103], v[102:103], v[152:153]
	v_cvt_pk_bf16_f32 v100, v100, v101
	v_cvt_pk_bf16_f32 v101, v102, v103
	v_pk_mul_f32 v[104:105], v[104:105], v[28:29]
	v_pk_mul_f32 v[106:107], v[106:107], v[30:31]
	v_pk_mul_f32 v[104:105], v[104:105], v[154:155]
	v_pk_mul_f32 v[106:107], v[106:107], v[156:157]
	v_cvt_pk_bf16_f32 v104, v104, v105
	v_cvt_pk_bf16_f32 v105, v106, v107
	v_pk_mul_f32 v[108:109], v[108:109], v[32:33]
	v_pk_mul_f32 v[110:111], v[110:111], v[34:35]
	v_pk_mul_f32 v[108:109], v[108:109], v[158:159]
	v_pk_mul_f32 v[110:111], v[110:111], v[160:161]
	v_cvt_pk_bf16_f32 v108, v108, v109
	v_cvt_pk_bf16_f32 v109, v110, v111
	global_store_dwordx2 v[58:59], v[96:97], off
	global_store_dwordx2 v[58:59], v[100:101], off offset:512
	global_store_dwordx2 v[58:59], v[104:105], off offset:1024
	global_store_dwordx2 v[58:59], v[108:109], off offset:1536
	s_waitcnt vmcnt(12)
	v_mul_f32_e32 v36, v113, v113
	v_fmac_f32_e32 v36, v112, v112
	v_fmac_f32_e32 v36, v114, v114
	v_fmac_f32_e32 v36, v115, v115
	v_mul_f32_e32 v37, v117, v117
	v_fmac_f32_e32 v37, v116, v116
	v_fmac_f32_e32 v37, v118, v118
	v_fmac_f32_e32 v37, v119, v119
	v_mul_f32_e32 v38, v121, v121
	v_fmac_f32_e32 v38, v120, v120
	v_fmac_f32_e32 v38, v122, v122
	v_fmac_f32_e32 v38, v123, v123
	v_mul_f32_e32 v39, v125, v125
	v_fmac_f32_e32 v39, v124, v124
	v_fmac_f32_e32 v39, v126, v126
	v_fmac_f32_e32 v39, v127, v127
	v_add_f32_e32 v165, v36, v37
	v_add_f32_e32 v165, v165, v38
	v_add_f32_e32 v165, v165, v39
	v_pk_mul_f32 v[112:113], v[112:113], v[20:21]
	v_pk_mul_f32 v[114:115], v[114:115], v[22:23]
	v_pk_mul_f32 v[112:113], v[112:113], v[146:147]
	v_pk_mul_f32 v[114:115], v[114:115], v[148:149]
	v_cvt_pk_bf16_f32 v112, v112, v113
	v_cvt_pk_bf16_f32 v113, v114, v115
	v_pk_mul_f32 v[116:117], v[116:117], v[24:25]
	v_pk_mul_f32 v[118:119], v[118:119], v[26:27]
	v_pk_mul_f32 v[116:117], v[116:117], v[150:151]
	v_pk_mul_f32 v[118:119], v[118:119], v[152:153]
	v_cvt_pk_bf16_f32 v116, v116, v117
	v_cvt_pk_bf16_f32 v117, v118, v119
	v_pk_mul_f32 v[120:121], v[120:121], v[28:29]
	v_pk_mul_f32 v[122:123], v[122:123], v[30:31]
	v_pk_mul_f32 v[120:121], v[120:121], v[154:155]
	v_pk_mul_f32 v[122:123], v[122:123], v[156:157]
	v_cvt_pk_bf16_f32 v120, v120, v121
	v_cvt_pk_bf16_f32 v121, v122, v123
	v_pk_mul_f32 v[124:125], v[124:125], v[32:33]
	v_pk_mul_f32 v[126:127], v[126:127], v[34:35]
	v_pk_mul_f32 v[124:125], v[124:125], v[158:159]
	v_pk_mul_f32 v[126:127], v[126:127], v[160:161]
	v_cvt_pk_bf16_f32 v124, v124, v125
	v_cvt_pk_bf16_f32 v125, v126, v127
	global_store_dwordx2 v[58:59], v[112:113], off offset:2048
	global_store_dwordx2 v[58:59], v[116:117], off offset:2560
	global_store_dwordx2 v[58:59], v[120:121], off offset:3072
	global_store_dwordx2 v[58:59], v[124:125], off offset:3584
	ds_bpermute_b32 v166, v4, v162
	ds_bpermute_b32 v167, v4, v163
	ds_bpermute_b32 v168, v4, v164
	ds_bpermute_b32 v169, v4, v165
	s_waitcnt lgkmcnt(0)
	v_add_f32_e32 v162, v162, v166
	v_add_f32_e32 v163, v163, v167
	v_add_f32_e32 v164, v164, v168
	v_add_f32_e32 v165, v165, v169
	ds_bpermute_b32 v166, v5, v162
	ds_bpermute_b32 v167, v5, v163
	ds_bpermute_b32 v168, v5, v164
	ds_bpermute_b32 v169, v5, v165
	s_waitcnt lgkmcnt(0)
	v_add_f32_e32 v162, v162, v166
	v_add_f32_e32 v163, v163, v167
	v_add_f32_e32 v164, v164, v168
	v_add_f32_e32 v165, v165, v169
	ds_bpermute_b32 v166, v6, v162
	ds_bpermute_b32 v167, v6, v163
	ds_bpermute_b32 v168, v6, v164
	ds_bpermute_b32 v169, v6, v165
	s_waitcnt lgkmcnt(0)
	v_add_f32_e32 v162, v162, v166
	v_add_f32_e32 v163, v163, v167
	v_add_f32_e32 v164, v164, v168
	v_add_f32_e32 v165, v165, v169
	ds_bpermute_b32 v166, v7, v162
	ds_bpermute_b32 v167, v7, v163
	ds_bpermute_b32 v168, v7, v164
	ds_bpermute_b32 v169, v7, v165
	s_waitcnt lgkmcnt(0)
	v_add_f32_e32 v162, v162, v166
	v_add_f32_e32 v163, v163, v167
	v_add_f32_e32 v164, v164, v168
	v_add_f32_e32 v165, v165, v169
	ds_bpermute_b32 v166, v8, v162
	ds_bpermute_b32 v167, v8, v163
	ds_bpermute_b32 v168, v8, v164
	ds_bpermute_b32 v169, v8, v165
	s_waitcnt lgkmcnt(0)
	v_add_f32_e32 v162, v162, v166
	v_add_f32_e32 v163, v163, v167
	v_add_f32_e32 v164, v164, v168
	v_add_f32_e32 v165, v165, v169
	ds_bpermute_b32 v166, v9, v162
	ds_bpermute_b32 v167, v9, v163
	ds_bpermute_b32 v168, v9, v164
	ds_bpermute_b32 v169, v9, v165
	s_waitcnt lgkmcnt(0)
	v_add_f32_e32 v162, v162, v166
	v_add_f32_e32 v163, v163, v167
	v_add_f32_e32 v164, v164, v168
	v_add_f32_e32 v165, v165, v169
	s_and_saveexec_b64 s[2:3], s[36:37]
	v_cndmask_b32_e64 v162, 0, v162, s[38:39]
	v_cndmask_b32_e64 v163, 0, v163, s[38:39]
	v_cndmask_b32_e64 v164, 0, v164, s[38:39]
	v_cndmask_b32_e64 v165, 0, v165, s[38:39]
	global_store_dword v[62:63], v162, off
	global_store_dword v[62:63], v163, off offset:128
	global_store_dword v[62:63], v164, off offset:256
	global_store_dword v[62:63], v165, off offset:384
	s_or_b64 exec, exec, s[2:3]
	v_readlane_b32 s40, v254, 57
	v_readlane_b32 s41, v254, 58
	v_readlane_b32 s42, v254, 59
	v_readlane_b32 s43, v254, 60
	v_readlane_b32 s44, v254, 61
	v_readlane_b32 s45, v254, 62
	v_readlane_b32 s46, v254, 63
	v_readlane_b32 s47, v255, 0
	v_readlane_b32 s48, v255, 1
	v_readlane_b32 s49, v255, 2
	v_readlane_b32 s50, v255, 3
	v_readlane_b32 s51, v255, 4
	v_readlane_b32 s52, v255, 5
	v_readlane_b32 s53, v255, 6
	v_readlane_b32 s54, v255, 7
	v_readlane_b32 s55, v255, 8
	v_mov_b32_e32 v10, 0

.LBB0_301:
	v_mul_f32_e32 v2, 0xbfb8aa3b, v1
	v_rndne_f32_e32 v3, v2
	s_mov_b32 s38, 0xbfb8aa3b
	v_sub_f32_e32 v4, v2, v3
	v_fma_f32 v2, v1, s38, -v2
	v_fmac_f32_e32 v2, 0xb2a5705f, v1
	v_add_f32_e32 v2, v4, v2
	v_exp_f32_e32 v2, v2
	v_cvt_i32_f32_e32 v3, v3
	s_mov_b32 s38, 0x42ce8ed0
	v_cmp_nlt_f32_e32 vcc, s38, v1
	s_mov_b32 s38, 0xc2b17218
	v_ldexp_f32 v2, v2, v3
	v_cndmask_b32_e32 v2, 0, v2, vcc
	v_cmp_ngt_f32_e32 vcc, s38, v1
	s_mov_b32 s38, 0x3f2aaaab
	s_sub_i32 s56, s55, s29
	v_cndmask_b32_e32 v1, v252, v2, vcc
	v_add_f32_e32 v2, 1.0, v1
	v_add_f32_e32 v4, -1.0, v2
	v_sub_f32_e32 v5, v4, v2
	v_add_f32_e32 v5, 1.0, v5
	v_sub_f32_e32 v4, v1, v4
	v_add_f32_e32 v6, v4, v5
	v_frexp_mant_f32_e32 v7, v2
	v_cvt_f64_f32_e32 v[4:5], v2
	v_frexp_exp_i32_f64_e32 v4, v[4:5]
	v_cmp_gt_f32_e32 vcc, s38, v7
	s_mov_b32 s38, 0x3f317218
	s_ashr_i32 s58, s56, 7
	v_subbrev_co_u32_e32 v4, vcc, 0, v4, vcc
	v_sub_u32_e32 v5, 0, v4
	v_ldexp_f32 v2, v2, v5
	v_ldexp_f32 v5, v6, v5
	v_add_f32_e32 v6, -1.0, v2
	v_add_f32_e32 v9, 1.0, v2
	v_add_f32_e32 v7, 1.0, v6
	v_add_f32_e32 v10, -1.0, v9
	v_sub_f32_e32 v7, v2, v7
	v_sub_f32_e32 v2, v2, v10
	v_add_f32_e32 v2, v5, v2
	v_add_f32_e32 v7, v5, v7
	v_add_f32_e32 v5, v9, v2
	v_rcp_f32_e32 v10, v5
	v_add_f32_e32 v8, v6, v7
	v_sub_f32_e32 v6, v6, v8
	v_add_f32_e32 v6, v7, v6
	v_sub_f32_e32 v7, v9, v5
	v_add_f32_e32 v2, v2, v7
	v_mul_f32_e32 v7, v8, v10
	v_mul_f32_e32 v9, v5, v7
	v_fma_f32 v11, v7, v5, -v9
	v_fmac_f32_e32 v11, v7, v2
	v_add_f32_e32 v12, v9, v11
	v_sub_f32_e32 v13, v8, v12
	v_sub_f32_e32 v8, v8, v13
	v_sub_f32_e32 v9, v12, v9
	v_sub_f32_e32 v8, v8, v12
	v_add_f32_e32 v6, v6, v8
	v_sub_f32_e32 v8, v9, v11
	v_add_f32_e32 v6, v8, v6
	v_add_f32_e32 v8, v13, v6
	v_mul_f32_e32 v9, v10, v8
	v_mul_f32_e32 v11, v5, v9
	v_fma_f32 v5, v9, v5, -v11
	v_fmac_f32_e32 v5, v9, v2
	v_sub_f32_e32 v2, v13, v8
	v_add_f32_e32 v2, v6, v2
	v_add_f32_e32 v6, v11, v5
	v_sub_f32_e32 v12, v8, v6
	v_sub_f32_e32 v8, v8, v12
	v_sub_f32_e32 v11, v6, v11
	v_sub_f32_e32 v6, v8, v6
	v_add_f32_e32 v2, v2, v6
	v_sub_f32_e32 v5, v11, v5
	v_cvt_f32_i32_e32 v4, v4
	v_add_f32_e32 v2, v5, v2
	v_add_f32_e32 v5, v7, v9
	v_add_f32_e32 v2, v12, v2
	v_sub_f32_e32 v6, v5, v7
	v_mul_f32_e32 v2, v10, v2
	v_sub_f32_e32 v6, v9, v6
	v_add_f32_e32 v2, v6, v2
	v_mul_f32_e32 v9, 0x3f317218, v4
	v_add_f32_e32 v6, v5, v2
	v_fma_f32 v10, v4, s38, -v9
	v_mul_f32_e32 v7, v6, v6
	v_fmac_f32_e32 v10, 0xb102e308, v4
	v_sub_f32_e32 v4, v6, v5
	v_fmamk_f32 v8, v7, 0x3e9b6dac, v251
	v_sub_f32_e32 v2, v2, v4
	v_add_f32_e32 v4, v9, v10
	v_fmaak_f32 v8, v7, v8, 0x3f2aaada
	v_sub_f32_e32 v5, v4, v9
	v_ldexp_f32 v9, v6, 1
	v_mul_f32_e32 v6, v6, v7
	v_mul_f32_e32 v6, v6, v8
	v_add_f32_e32 v7, v9, v6
	v_sub_f32_e32 v8, v7, v9
	v_ldexp_f32 v2, v2, 1
	v_sub_f32_e32 v6, v6, v8
	v_add_f32_e32 v2, v2, v6
	v_add_f32_e32 v6, v7, v2
	v_sub_f32_e32 v7, v6, v7
	v_sub_f32_e32 v2, v2, v7
	v_add_f32_e32 v7, v4, v6
	v_sub_f32_e32 v8, v7, v4
	v_sub_f32_e32 v9, v7, v8
	v_sub_f32_e32 v5, v10, v5
	v_sub_f32_e32 v4, v4, v9
	v_sub_f32_e32 v6, v6, v8
	v_add_f32_e32 v4, v6, v4
	v_add_f32_e32 v6, v5, v2
	v_sub_f32_e32 v8, v6, v5
	v_sub_f32_e32 v9, v6, v8
	v_sub_f32_e32 v5, v5, v9
	v_sub_f32_e32 v2, v2, v8
	v_add_f32_e32 v4, v6, v4
	v_add_f32_e32 v2, v2, v5
	v_add_f32_e32 v5, v7, v4
	s_not_b32 s59, s58
	v_sub_f32_e32 v6, v5, v7
	s_mov_b32 s38, 0x7f800000
	s_add_i32 s42, s28, s59
	v_sub_f32_e32 v4, v4, v6
	v_cmp_neq_f32_e32 vcc, s38, v1
	s_and_b64 s[38:39], s[36:37], exec
	v_add_f32_e32 v2, v2, v4
	s_cselect_b32 s38, s58, s42
	v_add_f32_e32 v2, v5, v2
	v_cvt_f32_i32_e32 v4, s38
	s_mov_b32 s38, 0x33800000
	v_cndmask_b32_e32 v2, v252, v2, vcc
	v_cmp_lt_f32_e64 vcc, |v1|, s38
	s_cmp_lg_u64 s[40:41], 0
	s_cselect_b64 s[44:45], -1, 0
	v_cndmask_b32_e32 v76, v2, v1, vcc
	v_mul_f32_e32 v71, 0xc3000000, v76
	v_mul_f32_e32 v1, v71, v4
	v_mul_f32_e32 v1, 0x3fb8aa3b, v1
	v_exp_f32_e32 v18, v1
	v_mov_b32_e32 v3, 0
	s_and_b64 vcc, exec, s[44:45]
	v_ashrrev_i32_e32 v1, 31, v0
	v_mov_b32_e32 v2, 0
	s_mov_b32 s74, s91
	v_mov_b32_e32 v4, 0
	v_mov_b32_e32 v5, 0
	v_mov_b32_e32 v6, 0
	v_mov_b32_e32 v7, 0
	v_mov_b32_e32 v8, 0
	v_mov_b32_e32 v9, 0
	v_mov_b32_e32 v10, 0
	v_mov_b32_e32 v11, 0
	v_mov_b32_e32 v12, 0
	v_mov_b32_e32 v13, 0
	v_mov_b32_e32 v14, 0
	v_mov_b32_e32 v15, 0
	v_mov_b32_e32 v16, 0
	v_mov_b32_e32 v17, 0
	s_cbranch_vccz .Lret_s0_skip
	v_lshl_add_u64 v[20:21], v[0:1], 2, s[40:41]
	global_load_dword v2, v[20:21], off
	global_load_dword v3, v[20:21], off offset:1024
	global_load_dword v4, v[20:21], off offset:2048
	global_load_dword v5, v[20:21], off offset:3072
	v_add_co_u32_e32 v20, vcc, 0x1000, v20
	s_nop 1
	v_addc_co_u32_e32 v21, vcc, 0, v21, vcc
	global_load_dword v6, v[20:21], off
	global_load_dword v7, v[20:21], off offset:1024
	global_load_dword v8, v[20:21], off offset:2048
	global_load_dword v9, v[20:21], off offset:3072
	v_add_co_u32_e32 v20, vcc, 0x1000, v20
	s_nop 1
	v_addc_co_u32_e32 v21, vcc, 0, v21, vcc
	global_load_dword v10, v[20:21], off
	global_load_dword v11, v[20:21], off offset:1024
	global_load_dword v12, v[20:21], off offset:2048
	global_load_dword v13, v[20:21], off offset:3072
	v_add_co_u32_e32 v20, vcc, 0x1000, v20
	s_nop 1
	v_addc_co_u32_e32 v21, vcc, 0, v21, vcc
	global_load_dword v14, v[20:21], off
	global_load_dword v15, v[20:21], off offset:1024
	global_load_dword v16, v[20:21], off offset:2048
	global_load_dword v17, v[20:21], off offset:3072
	s_waitcnt vmcnt(0)
	v_mul_f32_e32 v2, v18, v2
	v_mul_f32_e32 v3, v18, v3
	v_mul_f32_e32 v4, v18, v4
	v_mul_f32_e32 v5, v18, v5
	v_mul_f32_e32 v6, v18, v6
	v_mul_f32_e32 v7, v18, v7
	v_mul_f32_e32 v8, v18, v8
	v_mul_f32_e32 v9, v18, v9
	v_mul_f32_e32 v10, v18, v10
	v_mul_f32_e32 v11, v18, v11
	v_mul_f32_e32 v12, v18, v12
	v_mul_f32_e32 v13, v18, v13
	v_mul_f32_e32 v14, v18, v14
	v_mul_f32_e32 v15, v18, v15
	v_mul_f32_e32 v16, v18, v16
	v_mul_f32_e32 v17, v18, v17
.Lret_s0_skip:
.LBB0_333:
	s_ashr_i32 s29, s29, 7
	s_add_i32 s40, s58, 1
	s_and_b64 s[38:39], s[36:37], exec
	s_cselect_b32 s38, 0, s40
	s_cselect_b32 s39, s58, s28
	s_cmp_lt_i32 s38, s39
	s_cbranch_scc0 .LBB0_342
	s_lshl_b32 s41, s57, 1
	s_add_i32 s40, s39, -1
	s_add_i32 s41, s41, s90
	v_lshl_add_u64 v[18:19], v[0:1], 2, s[26:27]
	s_branch .LBB0_336

.LBB0_346:
	v_bfe_u32 v1, v0, 2, 1
	v_cmp_eq_u32_e64 s[38:39], 0, v1
	v_lshlrev_b32_e32 v200, 6, v1
	v_lshlrev_b32_e32 v1, 3, v0
	s_or_b32 s2, s44, s49
	v_lshl_add_u64 v[2:3], s[20:21], 0, v[200:201]
	v_and_b32_e32 v200, 24, v1
	v_lshl_add_u64 v[2:3], v[2:3], 0, v[200:201]
	s_lshl_b32 s94, s2, 1
	v_ashrrev_i32_e32 v1, 3, v0
	v_lshl_add_u64 v[16:17], v[2:3], 0, s[94:95]
	v_add_u32_e32 v2, s55, v1
	v_mad_i64_i32 v[10:11], s[2:3], v2, s92, v[16:17]
	s_mov_b64 s[2:3], 0x2c000
	v_lshl_add_u64 v[12:13], v[10:11], 0, s[2:3]
	v_lshl_add_u64 v[14:15], v[12:13], 0, s[2:3]
	v_lshl_add_u64 v[18:19], v[14:15], 0, s[2:3]
	global_load_dwordx2 v[128:129], v[10:11], off
	global_load_dwordx2 v[130:131], v[10:11], off offset:32
	global_load_dwordx2 v[132:133], v[10:11], off offset:512
	global_load_dwordx2 v[134:135], v[10:11], off offset:544
	global_load_dwordx2 v[136:137], v[12:13], off
	global_load_dwordx2 v[138:139], v[12:13], off offset:32
	global_load_dwordx2 v[140:141], v[12:13], off offset:512
	global_load_dwordx2 v[142:143], v[12:13], off offset:544
	global_load_dwordx2 v[144:145], v[14:15], off
	global_load_dwordx2 v[146:147], v[14:15], off offset:32
	global_load_dwordx2 v[148:149], v[14:15], off offset:512
	global_load_dwordx2 v[150:151], v[14:15], off offset:544
	global_load_dwordx2 v[152:153], v[18:19], off
	global_load_dwordx2 v[154:155], v[18:19], off offset:32
	global_load_dwordx2 v[156:157], v[18:19], off offset:512
	global_load_dwordx2 v[158:159], v[18:19], off offset:544
	v_add_u32_e32 v78, 32, v1
	v_add_u32_e32 v25, 64, v1
	v_add_u32_e32 v27, 0x60, v1
	s_and_b64 vcc, exec, s[0:1]
	s_cbranch_vccnz .Lqk_norot
	v_add_u32_e32 v72, s56, v1
	v_and_b32_e32 v73, 63, v72
	v_ashrrev_i32_e32 v72, 6, v72
	v_cndmask_b32_e64 v72, v73, v72, s[38:39]
	v_lshl_or_b32 v72, v72, 5, v200
	v_lshlrev_b32_e32 v79, 2, v72
	global_load_dwordx4 v[160:163], v79, s[12:13]
	global_load_dwordx4 v[164:167], v79, s[12:13] offset:16
	v_add_u32_e32 v72, s56, v78
	v_and_b32_e32 v73, 63, v72
	v_ashrrev_i32_e32 v72, 6, v72
	v_cndmask_b32_e64 v72, v73, v72, s[38:39]
	v_lshl_or_b32 v72, v72, 5, v200
	v_lshlrev_b32_e32 v80, 2, v72
	global_load_dwordx4 v[168:171], v80, s[12:13]
	global_load_dwordx4 v[172:175], v80, s[12:13] offset:16
	v_add_u32_e32 v72, s56, v25
	v_and_b32_e32 v73, 63, v72
	v_ashrrev_i32_e32 v72, 6, v72
	v_cndmask_b32_e64 v72, v73, v72, s[38:39]
	v_lshl_or_b32 v72, v72, 5, v200
	v_lshlrev_b32_e32 v81, 2, v72
	global_load_dwordx4 v[176:179], v81, s[12:13]
	global_load_dwordx4 v[180:183], v81, s[12:13] offset:16
	v_add_u32_e32 v72, s56, v27
	v_and_b32_e32 v73, 63, v72
	v_ashrrev_i32_e32 v72, 6, v72
	v_cndmask_b32_e64 v72, v73, v72, s[38:39]
	v_lshl_or_b32 v72, v72, 5, v200
	v_lshlrev_b32_e32 v82, 2, v72
	global_load_dwordx4 v[184:187], v82, s[12:13]
	global_load_dwordx4 v[188:191], v82, s[12:13] offset:16
	s_waitcnt vmcnt(0)
	v_lshlrev_b32_e32 v72, 16, v128
	v_lshlrev_b32_e32 v73, 16, v130
	v_mul_f32_e32 v74, v73, v161
	v_mul_f32_e32 v75, v72, v161
	v_fma_f32 v8, v72, v160, -v74
	v_fma_f32 v2, v73, v160, v75
	v_and_b32_e32 v72, 0xffff0000, v128
	v_and_b32_e32 v73, 0xffff0000, v130
	v_mul_f32_e32 v74, v73, v163
	v_mul_f32_e32 v75, v72, v163
	v_fma_f32 v9, v72, v162, -v74
	v_fma_f32 v3, v73, v162, v75
	v_lshlrev_b32_e32 v72, 16, v129
	v_lshlrev_b32_e32 v73, 16, v131
	v_mul_f32_e32 v74, v73, v165
	v_mul_f32_e32 v75, v72, v165
	v_fma_f32 v4, v72, v164, -v74
	v_fma_f32 v6, v73, v164, v75
	v_and_b32_e32 v72, 0xffff0000, v129
	v_and_b32_e32 v73, 0xffff0000, v131
	v_mul_f32_e32 v74, v73, v167
	v_mul_f32_e32 v75, v72, v167
	v_fma_f32 v5, v72, v166, -v74
	v_fma_f32 v7, v73, v166, v75
	v_lshlrev_b32_e32 v72, 16, v132
	v_lshlrev_b32_e32 v73, 16, v134
	v_mul_f32_e32 v74, v73, v161
	v_mul_f32_e32 v75, v72, v161
	v_fma_f32 v18, v72, v160, -v74
	v_fma_f32 v10, v73, v160, v75
	v_and_b32_e32 v72, 0xffff0000, v132
	v_and_b32_e32 v73, 0xffff0000, v134
	v_mul_f32_e32 v74, v73, v163
	v_mul_f32_e32 v75, v72, v163
	v_fma_f32 v19, v72, v162, -v74
	v_fma_f32 v11, v73, v162, v75
	v_lshlrev_b32_e32 v72, 16, v133
	v_lshlrev_b32_e32 v73, 16, v135
	v_mul_f32_e32 v74, v73, v165
	v_mul_f32_e32 v75, v72, v165
	v_fma_f32 v14, v72, v164, -v74
	v_fma_f32 v12, v73, v164, v75
	v_and_b32_e32 v72, 0xffff0000, v133
	v_and_b32_e32 v73, 0xffff0000, v135
	v_mul_f32_e32 v74, v73, v167
	v_mul_f32_e32 v75, v72, v167
	v_fma_f32 v15, v72, v166, -v74
	v_fma_f32 v13, v73, v166, v75
	v_lshlrev_b32_e32 v72, 16, v136
	v_lshlrev_b32_e32 v73, 16, v138
	v_mul_f32_e32 v74, v73, v169
	v_mul_f32_e32 v75, v72, v169
	v_fma_f32 v22, v72, v168, -v74
	v_fma_f32 v20, v73, v168, v75
	v_and_b32_e32 v72, 0xffff0000, v136
	v_and_b32_e32 v73, 0xffff0000, v138
	v_mul_f32_e32 v74, v73, v171
	v_mul_f32_e32 v75, v72, v171
	v_fma_f32 v23, v72, v170, -v74
	v_fma_f32 v21, v73, v170, v75
	v_lshlrev_b32_e32 v72, 16, v137
	v_lshlrev_b32_e32 v73, 16, v139
	v_mul_f32_e32 v74, v73, v173
	v_mul_f32_e32 v75, v72, v173
	v_fma_f32 v24, v72, v172, -v74
	v_fma_f32 v26, v73, v172, v75
	v_and_b32_e32 v72, 0xffff0000, v137
	v_and_b32_e32 v73, 0xffff0000, v139
	v_mul_f32_e32 v74, v73, v175
	v_mul_f32_e32 v75, v72, v175
	v_fma_f32 v28, v72, v174, -v74
	v_fma_f32 v29, v73, v174, v75
	v_lshlrev_b32_e32 v72, 16, v140
	v_lshlrev_b32_e32 v73, 16, v142
	v_mul_f32_e32 v74, v73, v169
	v_mul_f32_e32 v75, v72, v169
	v_fma_f32 v32, v72, v168, -v74
	v_fma_f32 v30, v73, v168, v75
	v_and_b32_e32 v72, 0xffff0000, v140
	v_and_b32_e32 v73, 0xffff0000, v142
	v_mul_f32_e32 v74, v73, v171
	v_mul_f32_e32 v75, v72, v171
	v_fma_f32 v33, v72, v170, -v74
	v_fma_f32 v31, v73, v170, v75
	v_lshlrev_b32_e32 v72, 16, v141
	v_lshlrev_b32_e32 v73, 16, v143
	v_mul_f32_e32 v74, v73, v173
	v_mul_f32_e32 v75, v72, v173
	v_fma_f32 v36, v72, v172, -v74
	v_fma_f32 v34, v73, v172, v75
	v_and_b32_e32 v72, 0xffff0000, v141
	v_and_b32_e32 v73, 0xffff0000, v143
	v_mul_f32_e32 v74, v73, v175
	v_mul_f32_e32 v75, v72, v175
	v_fma_f32 v37, v72, v174, -v74
	v_fma_f32 v35, v73, v174, v75
	v_lshlrev_b32_e32 v72, 16, v144
	v_lshlrev_b32_e32 v73, 16, v146
	v_mul_f32_e32 v74, v73, v177
	v_mul_f32_e32 v75, v72, v177
	v_fma_f32 v40, v72, v176, -v74
	v_fma_f32 v38, v73, v176, v75
	v_and_b32_e32 v72, 0xffff0000, v144
	v_and_b32_e32 v73, 0xffff0000, v146
	v_mul_f32_e32 v74, v73, v179
	v_mul_f32_e32 v75, v72, v179
	v_fma_f32 v41, v72, v178, -v74
	v_fma_f32 v39, v73, v178, v75
	v_lshlrev_b32_e32 v72, 16, v145
	v_lshlrev_b32_e32 v73, 16, v147
	v_mul_f32_e32 v74, v73, v181
	v_mul_f32_e32 v75, v72, v181
	v_fma_f32 v42, v72, v180, -v74
	v_fma_f32 v44, v73, v180, v75
	v_and_b32_e32 v72, 0xffff0000, v145
	v_and_b32_e32 v73, 0xffff0000, v147
	v_mul_f32_e32 v74, v73, v183
	v_mul_f32_e32 v75, v72, v183
	v_fma_f32 v46, v72, v182, -v74
	v_fma_f32 v47, v73, v182, v75
	v_lshlrev_b32_e32 v72, 16, v148
	v_lshlrev_b32_e32 v73, 16, v150
	v_mul_f32_e32 v74, v73, v177
	v_mul_f32_e32 v75, v72, v177
	v_fma_f32 v50, v72, v176, -v74
	v_fma_f32 v48, v73, v176, v75
	v_and_b32_e32 v72, 0xffff0000, v148
	v_and_b32_e32 v73, 0xffff0000, v150
	v_mul_f32_e32 v74, v73, v179
	v_mul_f32_e32 v75, v72, v179
	v_fma_f32 v51, v72, v178, -v74
	v_fma_f32 v49, v73, v178, v75
	v_lshlrev_b32_e32 v72, 16, v149
	v_lshlrev_b32_e32 v73, 16, v151
	v_mul_f32_e32 v74, v73, v181
	v_mul_f32_e32 v75, v72, v181
	v_fma_f32 v54, v72, v180, -v74
	v_fma_f32 v52, v73, v180, v75
	v_and_b32_e32 v72, 0xffff0000, v149
	v_and_b32_e32 v73, 0xffff0000, v151
	v_mul_f32_e32 v74, v73, v183
	v_mul_f32_e32 v75, v72, v183
	v_fma_f32 v55, v72, v182, -v74
	v_fma_f32 v53, v73, v182, v75
	v_lshlrev_b32_e32 v72, 16, v152
	v_lshlrev_b32_e32 v73, 16, v154
	v_mul_f32_e32 v74, v73, v185
	v_mul_f32_e32 v75, v72, v185
	v_fma_f32 v56, v72, v184, -v74
	v_fma_f32 v16, v73, v184, v75
	v_and_b32_e32 v72, 0xffff0000, v152
	v_and_b32_e32 v73, 0xffff0000, v154
	v_mul_f32_e32 v74, v73, v187
	v_mul_f32_e32 v75, v72, v187
	v_fma_f32 v57, v72, v186, -v74
	v_fma_f32 v17, v73, v186, v75
	v_lshlrev_b32_e32 v72, 16, v153
	v_lshlrev_b32_e32 v73, 16, v155
	v_mul_f32_e32 v74, v73, v189
	v_mul_f32_e32 v75, v72, v189
	v_fma_f32 v58, v72, v188, -v74
	v_fma_f32 v60, v73, v188, v75
	v_and_b32_e32 v72, 0xffff0000, v153
	v_and_b32_e32 v73, 0xffff0000, v155
	v_mul_f32_e32 v74, v73, v191
	v_mul_f32_e32 v75, v72, v191
	v_fma_f32 v62, v72, v190, -v74
	v_fma_f32 v63, v73, v190, v75
	v_lshlrev_b32_e32 v72, 16, v156
	v_lshlrev_b32_e32 v73, 16, v158
	v_mul_f32_e32 v74, v73, v185
	v_mul_f32_e32 v75, v72, v185
	v_fma_f32 v66, v72, v184, -v74
	v_fma_f32 v64, v73, v184, v75
	v_and_b32_e32 v72, 0xffff0000, v156
	v_and_b32_e32 v73, 0xffff0000, v158
	v_mul_f32_e32 v74, v73, v187
	v_mul_f32_e32 v75, v72, v187
	v_fma_f32 v67, v72, v186, -v74
	v_fma_f32 v65, v73, v186, v75
	v_lshlrev_b32_e32 v72, 16, v157
	v_lshlrev_b32_e32 v73, 16, v159
	v_mul_f32_e32 v74, v73, v189
	v_mul_f32_e32 v75, v72, v189
	v_fma_f32 v70, v72, v188, -v74
	v_fma_f32 v68, v73, v188, v75
	v_and_b32_e32 v72, 0xffff0000, v157
	v_and_b32_e32 v73, 0xffff0000, v159
	v_mul_f32_e32 v74, v73, v191
	v_mul_f32_e32 v75, v72, v191
	v_fma_f32 v71, v72, v190, -v74
	v_fma_f32 v69, v73, v190, v75
	s_branch .Lqk_done
.Lqk_norot:
	s_waitcnt vmcnt(0)
	v_lshlrev_b32_e32 v8, 16, v128
	v_lshlrev_b32_e32 v2, 16, v130
	v_and_b32_e32 v9, 0xffff0000, v128
	v_and_b32_e32 v3, 0xffff0000, v130
	v_lshlrev_b32_e32 v4, 16, v129
	v_lshlrev_b32_e32 v6, 16, v131
	v_and_b32_e32 v5, 0xffff0000, v129
	v_and_b32_e32 v7, 0xffff0000, v131
	v_lshlrev_b32_e32 v18, 16, v132
	v_lshlrev_b32_e32 v10, 16, v134
	v_and_b32_e32 v19, 0xffff0000, v132
	v_and_b32_e32 v11, 0xffff0000, v134
	v_lshlrev_b32_e32 v14, 16, v133
	v_lshlrev_b32_e32 v12, 16, v135
	v_and_b32_e32 v15, 0xffff0000, v133
	v_and_b32_e32 v13, 0xffff0000, v135
	v_lshlrev_b32_e32 v22, 16, v136
	v_lshlrev_b32_e32 v20, 16, v138
	v_and_b32_e32 v23, 0xffff0000, v136
	v_and_b32_e32 v21, 0xffff0000, v138
	v_lshlrev_b32_e32 v24, 16, v137
	v_lshlrev_b32_e32 v26, 16, v139
	v_and_b32_e32 v28, 0xffff0000, v137
	v_and_b32_e32 v29, 0xffff0000, v139
	v_lshlrev_b32_e32 v32, 16, v140
	v_lshlrev_b32_e32 v30, 16, v142
	v_and_b32_e32 v33, 0xffff0000, v140
	v_and_b32_e32 v31, 0xffff0000, v142
	v_lshlrev_b32_e32 v36, 16, v141
	v_lshlrev_b32_e32 v34, 16, v143
	v_and_b32_e32 v37, 0xffff0000, v141
	v_and_b32_e32 v35, 0xffff0000, v143
	v_lshlrev_b32_e32 v40, 16, v144
	v_lshlrev_b32_e32 v38, 16, v146
	v_and_b32_e32 v41, 0xffff0000, v144
	v_and_b32_e32 v39, 0xffff0000, v146
	v_lshlrev_b32_e32 v42, 16, v145
	v_lshlrev_b32_e32 v44, 16, v147
	v_and_b32_e32 v46, 0xffff0000, v145
	v_and_b32_e32 v47, 0xffff0000, v147
	v_lshlrev_b32_e32 v50, 16, v148
	v_lshlrev_b32_e32 v48, 16, v150
	v_and_b32_e32 v51, 0xffff0000, v148
	v_and_b32_e32 v49, 0xffff0000, v150
	v_lshlrev_b32_e32 v54, 16, v149
	v_lshlrev_b32_e32 v52, 16, v151
	v_and_b32_e32 v55, 0xffff0000, v149
	v_and_b32_e32 v53, 0xffff0000, v151
	v_lshlrev_b32_e32 v56, 16, v152
	v_lshlrev_b32_e32 v16, 16, v154
	v_and_b32_e32 v57, 0xffff0000, v152
	v_and_b32_e32 v17, 0xffff0000, v154
	v_lshlrev_b32_e32 v58, 16, v153
	v_lshlrev_b32_e32 v60, 16, v155
	v_and_b32_e32 v62, 0xffff0000, v153
	v_and_b32_e32 v63, 0xffff0000, v155
	v_lshlrev_b32_e32 v66, 16, v156
	v_lshlrev_b32_e32 v64, 16, v158
	v_and_b32_e32 v67, 0xffff0000, v156
	v_and_b32_e32 v65, 0xffff0000, v158
	v_lshlrev_b32_e32 v70, 16, v157
	v_lshlrev_b32_e32 v68, 16, v159
	v_and_b32_e32 v71, 0xffff0000, v157
	v_and_b32_e32 v69, 0xffff0000, v159
.Lqk_done:
	s_movk_i32 s28, 0x90

.LBB0_394:
	s_and_b32 s2, s33, -2
	s_add_i32 s2, s2, s90
	s_and_b32 s38, s2, 3
	s_or_b32 s28, s38, s75
	v_mov_b32_e32 v0, v229
	s_ashr_i32 s29, s28, 31
	s_lshl_b64 s[0:1], s[28:29], 16
	v_and_b32_e32 v116, 15, v0
	v_readlane_b32 s40, v253, 3
	v_ashrrev_i32_e32 v6, 6, v0
	v_bfe_u32 v117, v0, 4, 2
	v_readlane_b32 s41, v253, 4
	s_add_u32 s0, s40, s0
	v_lshlrev_b32_e32 v2, 7, v116
	s_addc_u32 s1, s41, s1
	v_lshlrev_b32_e32 v200, 5, v117
	v_lshl_or_b32 v2, v6, 12, v2
	s_waitcnt lgkmcnt(0)
	v_lshl_add_u64 v[0:1], s[0:1], 0, v[200:201]
	v_ashrrev_i32_e32 v3, 31, v2
	v_lshl_add_u64 v[4:5], v[2:3], 2, v[0:1]
	v_or_b32_e32 v2, 0x800, v2
	v_ashrrev_i32_e32 v3, 31, v2
	s_lshl_b32 s3, s2, 5
	s_waitcnt vmcnt(0)
	v_lshlrev_b32_e32 v104, 5, v6
	v_lshlrev_b32_e32 v105, 2, v117
	v_lshl_add_u64 v[0:1], v[2:3], 2, v[0:1]
	s_and_b32 s0, s3, 0xffffff80
	v_or_b32_e32 v2, v105, v104
	v_add_u32_e32 v88, s0, v2
	v_mov_b64_e32 v[72:73], s[20:21]
	global_load_dwordx4 v[56:59], v[4:5], off offset:16
	global_load_dwordx4 v[60:63], v[4:5], off
	global_load_dwordx4 v[64:67], v[0:1], off offset:16
	global_load_dwordx4 v[68:71], v[0:1], off
	global_load_dwordx4 v[44:47], v[4:5], off offset:144
	global_load_dwordx4 v[52:55], v[4:5], off offset:128
	global_load_dwordx4 v[40:43], v[0:1], off offset:144
	global_load_dwordx4 v[48:51], v[0:1], off offset:128
	global_load_dwordx4 v[28:31], v[4:5], off offset:272
	global_load_dwordx4 v[36:39], v[4:5], off offset:256
	global_load_dwordx4 v[24:27], v[0:1], off offset:272
	global_load_dwordx4 v[32:35], v[0:1], off offset:256
	global_load_dwordx4 v[12:15], v[4:5], off offset:400
	global_load_dwordx4 v[20:23], v[4:5], off offset:384
	global_load_dwordx4 v[8:11], v[0:1], off offset:400
	global_load_dwordx4 v[16:19], v[0:1], off offset:384
	v_lshl_add_u32 v0, s28, 7, v2
	v_mad_i64_i32 v[2:3], s[28:29], v88, s92, v[72:73]
	s_lshl_b32 s94, s38, 7
	v_lshl_add_u64 v[2:3], v[2:3], 0, s[94:95]
	v_lshlrev_b32_e32 v200, 1, v116
	v_lshl_add_u64 v[74:75], v[2:3], 0, v[200:201]
	v_or_b32_e32 v2, 1, v88
	v_mad_i64_i32 v[2:3], s[28:29], v2, s92, v[72:73]
	v_lshl_add_u64 v[2:3], v[2:3], 0, s[94:95]
	v_lshl_add_u64 v[76:77], v[2:3], 0, v[200:201]
	v_or_b32_e32 v2, 2, v88
	v_or_b32_e32 v86, 18, v88
	v_mad_i64_i32 v[2:3], s[28:29], v2, s92, v[72:73]
	v_mad_i64_i32 v[86:87], s[28:29], v86, s92, v[72:73]
	v_lshl_add_u64 v[2:3], v[2:3], 0, s[94:95]
	v_lshl_add_u64 v[86:87], v[86:87], 0, s[94:95]
	v_lshl_add_u64 v[78:79], v[2:3], 0, v[200:201]
	v_or_b32_e32 v2, 3, v88
	v_or_b32_e32 v82, 16, v88
	v_or_b32_e32 v84, 17, v88
	v_lshl_add_u64 v[118:119], v[86:87], 0, v[200:201]
	v_or_b32_e32 v86, 19, v88
	v_mad_i64_i32 v[2:3], s[28:29], v2, s92, v[72:73]
	v_mad_i64_i32 v[82:83], s[28:29], v82, s92, v[72:73]
	v_mad_i64_i32 v[84:85], s[28:29], v84, s92, v[72:73]
	v_mad_i64_i32 v[72:73], s[28:29], v86, s92, v[72:73]
	v_readlane_b32 s42, v253, 5
	v_readlane_b32 s43, v253, 6
	v_ashrrev_i32_e32 v1, 31, v0
	v_lshl_add_u64 v[82:83], v[82:83], 0, s[94:95]
	v_lshl_add_u64 v[84:85], v[84:85], 0, s[94:95]
	v_lshl_add_u64 v[72:73], v[72:73], 0, s[94:95]
	s_mul_i32 s28, s0, 0x1600
	v_lshl_add_u64 v[0:1], v[0:1], 2, s[42:43]
	v_lshl_add_u64 v[2:3], v[2:3], 0, s[94:95]
	v_lshl_add_u64 v[82:83], v[82:83], 0, v[200:201]
	v_lshl_add_u64 v[84:85], v[84:85], 0, v[200:201]
	v_lshl_add_u64 v[72:73], v[72:73], 0, v[200:201]
	s_mul_hi_i32 s1, s0, 0x1600
	s_add_u32 s28, s20, s28
	v_mov_b32_e32 v124, v229
	global_load_dwordx4 v[4:7], v[0:1], off
	v_lshl_add_u64 v[80:81], v[2:3], 0, v[200:201]
	global_load_dwordx4 v[0:3], v[0:1], off offset:64
	s_addc_u32 s1, s21, s1
	global_load_ushort v115, v[74:75], off offset:1024
	global_load_ushort v114, v[74:75], off offset:1056
	global_load_ushort v113, v[74:75], off offset:1088
	global_load_ushort v112, v[74:75], off offset:1120
	global_load_ushort v111, v[76:77], off offset:1024
	global_load_ushort v110, v[76:77], off offset:1056
	global_load_ushort v109, v[76:77], off offset:1088
	global_load_ushort v108, v[76:77], off offset:1120
	global_load_ushort v107, v[78:79], off offset:1024
	global_load_ushort v106, v[78:79], off offset:1056
	global_load_ushort v103, v[78:79], off offset:1088
	global_load_ushort v102, v[78:79], off offset:1120
	global_load_ushort v101, v[80:81], off offset:1024
	global_load_ushort v100, v[80:81], off offset:1056
	global_load_ushort v99, v[80:81], off offset:1088
	global_load_ushort v98, v[80:81], off offset:1120
	global_load_ushort v97, v[82:83], off offset:1024
	global_load_ushort v96, v[82:83], off offset:1056
	global_load_ushort v95, v[82:83], off offset:1088
	global_load_ushort v94, v[82:83], off offset:1120
	global_load_ushort v93, v[84:85], off offset:1024
	global_load_ushort v92, v[84:85], off offset:1056
	global_load_ushort v91, v[84:85], off offset:1088
	global_load_ushort v90, v[84:85], off offset:1120
	global_load_ushort v89, v[118:119], off offset:1024
	global_load_ushort v88, v[118:119], off offset:1056
	global_load_ushort v87, v[118:119], off offset:1088
	global_load_ushort v86, v[118:119], off offset:1120
	s_nop 0
	global_load_ushort v85, v[72:73], off offset:1024
	global_load_ushort v84, v[72:73], off offset:1056
	global_load_ushort v83, v[72:73], off offset:1088
	global_load_ushort v82, v[72:73], off offset:1120
	s_add_u32 s28, s28, s94
	v_lshlrev_b32_e32 v72, 2, v124
	v_and_b32_e32 v125, 60, v72
	s_addc_u32 s29, s1, 0
	v_lshlrev_b32_e32 v72, 1, v125
	v_mov_b32_e32 v73, v201
	v_lshl_add_u64 v[72:73], s[28:29], 0, v[72:73]
	v_ashrrev_i32_e32 v74, 4, v124
	v_mad_i64_i32 v[118:119], s[28:29], v74, s92, v[72:73]
	global_load_dwordx2 v[118:119], v[118:119], off offset:1536
	v_add_u32_e32 v126, 0x100, v124
	v_ashrrev_i32_e32 v74, 4, v126
	v_add_u32_e32 v127, 0x200, v124
	v_mad_i64_i32 v[120:121], s[28:29], v74, s92, v[72:73]
	v_ashrrev_i32_e32 v74, 4, v127
	v_add_u32_e32 v128, 0x300, v124
	v_mad_i64_i32 v[122:123], s[28:29], v74, s92, v[72:73]
	v_ashrrev_i32_e32 v74, 4, v128
	v_add_u32_e32 v129, 0x400, v124
	v_mad_i64_i32 v[80:81], s[28:29], v74, s92, v[72:73]
	v_ashrrev_i32_e32 v74, 4, v129
	v_add_u32_e32 v130, 0x500, v124
	v_mad_i64_i32 v[78:79], s[28:29], v74, s92, v[72:73]
	v_ashrrev_i32_e32 v74, 4, v130
	v_add_u32_e32 v131, 0x600, v124
	v_add_u32_e32 v132, 0x700, v124
	v_mad_i64_i32 v[76:77], s[28:29], v74, s92, v[72:73]
	v_ashrrev_i32_e32 v74, 4, v131
	v_ashrrev_i32_e32 v133, 4, v132
	v_mad_i64_i32 v[74:75], s[28:29], v74, s92, v[72:73]
	v_mad_i64_i32 v[72:73], s[28:29], v133, s92, v[72:73]
	global_load_dwordx2 v[120:121], v[120:121], off offset:1536
	global_load_dwordx2 v[122:123], v[122:123], off offset:1536
	global_load_dwordx2 v[80:81], v[80:81], off offset:1536
	global_load_dwordx2 v[78:79], v[78:79], off offset:1536
	global_load_dwordx2 v[76:77], v[76:77], off offset:1536
	global_load_dwordx2 v[74:75], v[74:75], off offset:1536
	global_load_dwordx2 v[72:73], v[72:73], off offset:1536
	v_mov_b32_e32 v133, s69
	s_movk_i32 s1, 0x110
	v_ashrrev_i32_e32 v124, 3, v124
	v_mad_u32_u24 v125, v125, s1, v133
	v_and_b32_e32 v124, -2, v124
	v_add_u32_e32 v124, v125, v124
	s_waitcnt vmcnt(0)
	ds_write_b16 v124, v118
	ds_write_b16_d16_hi v124, v118 offset:272
	ds_write_b16 v124, v119 offset:544
	ds_write_b16_d16_hi v124, v119 offset:816
	v_ashrrev_i32_e32 v118, 3, v126
	v_and_b32_e32 v118, -2, v118
	v_add_u32_e32 v124, v125, v118
	v_cvt_pk_bf16_f32 v60, v60, v61
	v_cvt_pk_bf16_f32 v61, v62, v63
	v_cvt_pk_bf16_f32 v63, v58, v59
	v_cvt_pk_bf16_f32 v58, v64, v65
	v_mul_u32_u24_e32 v64, 0x110, v116
	v_cvt_pk_bf16_f32 v62, v56, v57
	v_cvt_pk_bf16_f32 v56, v68, v69
	v_cvt_pk_bf16_f32 v57, v70, v71
	v_cvt_pk_bf16_f32 v59, v66, v67
	s_waitcnt vmcnt(0)
	ds_write_b16 v124, v120
	ds_write_b16_d16_hi v124, v120 offset:272
	ds_write_b16 v124, v121 offset:544
	ds_write_b16_d16_hi v124, v121 offset:816
	v_ashrrev_i32_e32 v118, 3, v127
	v_and_b32_e32 v118, -2, v118
	v_add_u32_e32 v120, v125, v118
	v_cvt_pk_bf16_f32 v52, v52, v53
	v_cvt_pk_bf16_f32 v53, v54, v55
	v_cvt_pk_bf16_f32 v54, v44, v45
	v_cvt_pk_bf16_f32 v55, v46, v47
	v_cvt_pk_bf16_f32 v44, v48, v49
	v_cvt_pk_bf16_f32 v45, v50, v51
	v_cvt_pk_bf16_f32 v46, v40, v41
	s_waitcnt vmcnt(0)
	ds_write_b16 v120, v122
	ds_write_b16_d16_hi v120, v122 offset:272
	ds_write_b16 v120, v123 offset:544
	ds_write_b16_d16_hi v120, v123 offset:816
	v_ashrrev_i32_e32 v118, 3, v128
	v_and_b32_e32 v118, -2, v118
	v_add_u32_e32 v118, v125, v118
	v_cvt_pk_bf16_f32 v47, v42, v43
	v_cvt_pk_bf16_f32 v36, v36, v37
	v_cvt_pk_bf16_f32 v37, v38, v39
	v_cvt_pk_bf16_f32 v38, v28, v29
	s_waitcnt vmcnt(0)
	ds_write_b16 v118, v80
	ds_write_b16_d16_hi v118, v80 offset:272
	ds_write_b16 v118, v81 offset:544
	ds_write_b16_d16_hi v118, v81 offset:816
	v_ashrrev_i32_e32 v80, 3, v129
	v_and_b32_e32 v80, -2, v80
	v_add_u32_e32 v80, v125, v80
	v_cvt_pk_bf16_f32 v39, v30, v31
	v_cvt_pk_bf16_f32 v28, v32, v33
	v_cvt_pk_bf16_f32 v29, v34, v35
	v_cvt_pk_bf16_f32 v30, v24, v25
	s_waitcnt vmcnt(0)
	ds_write_b16 v80, v78
	ds_write_b16_d16_hi v80, v78 offset:272
	ds_write_b16 v80, v79 offset:544
	ds_write_b16_d16_hi v80, v79 offset:816
	v_ashrrev_i32_e32 v78, 3, v130
	v_and_b32_e32 v78, -2, v78
	v_add_u32_e32 v78, v125, v78
	v_cvt_pk_bf16_f32 v31, v26, v27
	v_cvt_pk_bf16_f32 v20, v20, v21
	v_cvt_pk_bf16_f32 v21, v22, v23
	v_cvt_pk_bf16_f32 v22, v12, v13
	s_waitcnt vmcnt(0)
	ds_write_b16 v78, v76
	ds_write_b16_d16_hi v78, v76 offset:272
	ds_write_b16 v78, v77 offset:544
	ds_write_b16_d16_hi v78, v77 offset:816
	v_ashrrev_i32_e32 v76, 3, v131
	v_and_b32_e32 v76, -2, v76
	v_add_u32_e32 v76, v125, v76
	v_cvt_pk_bf16_f32 v23, v14, v15
	v_cvt_pk_bf16_f32 v12, v16, v17
	v_cvt_pk_bf16_f32 v13, v18, v19
	v_cvt_pk_bf16_f32 v14, v8, v9
	s_waitcnt vmcnt(0)
	ds_write_b16 v76, v74
	ds_write_b16_d16_hi v76, v74 offset:272
	ds_write_b16 v76, v75 offset:544
	ds_write_b16_d16_hi v76, v75 offset:816
	v_ashrrev_i32_e32 v74, 3, v132
	v_and_b32_e32 v74, -2, v74
	v_add_u32_e32 v74, v125, v74
	v_cvt_pk_bf16_f32 v15, v10, v11
	v_readlane_b32 s48, v253, 11
	v_readlane_b32 s49, v253, 12
	v_readlane_b32 s50, v253, 13
	s_waitcnt vmcnt(0)
	ds_write_b16 v74, v72
	ds_write_b16_d16_hi v74, v72 offset:272
	ds_write_b16 v74, v73 offset:544
	ds_write_b16_d16_hi v74, v73 offset:816
	v_lshlrev_b32_e32 v72, 4, v117
	s_waitcnt lgkmcnt(0)
	s_barrier
	v_add3_u32 v80, s69, v72, v64
	ds_read_b128 v[64:67], v80
	ds_read_b128 v[68:71], v80 offset:4352
	ds_read_b128 v[72:75], v80 offset:8704
	ds_read_b128 v[76:79], v80 offset:13056
	s_waitcnt lgkmcnt(3)
	v_mfma_f32_16x16x32_bf16 v[116:119], v[60:63], v[64:67], 0
	v_readlane_b32 s51, v253, 14
	v_readlane_b32 s52, v253, 15
	v_readlane_b32 s53, v253, 16
	s_waitcnt lgkmcnt(2)
	v_mfma_f32_16x16x32_bf16 v[120:123], v[60:63], v[68:71], 0
	v_readlane_b32 s54, v253, 17
	v_readlane_b32 s55, v253, 18
	v_readlane_b32 s48, v254, 57
	s_waitcnt lgkmcnt(1)
	v_mfma_f32_16x16x32_bf16 v[124:127], v[60:63], v[72:75], 0
	v_readlane_b32 s60, v255, 5
	v_readlane_b32 s61, v255, 6
	v_readlane_b32 s46, v253, 9
	s_waitcnt lgkmcnt(0)
	v_mfma_f32_16x16x32_bf16 v[60:63], v[60:63], v[76:79], 0
	v_readlane_b32 s47, v253, 10
	v_readlane_b32 s44, v253, 7
	v_readlane_b32 s45, v253, 8
	v_mfma_f32_16x16x32_bf16 v[64:67], v[56:59], v[64:67], 0
	v_readlane_b32 s49, v254, 58
	v_readlane_b32 s50, v254, 59
	v_readlane_b32 s51, v254, 60
	v_mfma_f32_16x16x32_bf16 v[68:71], v[56:59], v[68:71], 0
	v_readlane_b32 s52, v254, 61
	v_readlane_b32 s53, v254, 62
	v_readlane_b32 s54, v254, 63
	v_mfma_f32_16x16x32_bf16 v[72:75], v[56:59], v[72:75], 0
	v_readlane_b32 s55, v255, 0
	v_readlane_b32 s56, v255, 1
	v_readlane_b32 s57, v255, 2
	v_mfma_f32_16x16x32_bf16 v[56:59], v[56:59], v[76:79], 0
	ds_read_b128 v[40:43], v80 offset:64
	ds_read_b128 v[48:51], v80 offset:4416
	ds_read_b128 v[76:79], v80 offset:8768
	ds_read_b128 v[128:131], v80 offset:13120
	v_readlane_b32 s58, v255, 3
	v_readlane_b32 s59, v255, 4
	s_waitcnt lgkmcnt(3)
	v_mfma_f32_16x16x32_bf16 v[116:119], v[52:55], v[40:43], v[116:119]
	v_readlane_b32 s62, v255, 7
	v_readlane_b32 s63, v255, 8
	s_waitcnt lgkmcnt(2)
	v_mfma_f32_16x16x32_bf16 v[120:123], v[52:55], v[48:51], v[120:123]
	s_waitcnt lgkmcnt(1)
	v_mfma_f32_16x16x32_bf16 v[124:127], v[52:55], v[76:79], v[124:127]
	s_waitcnt lgkmcnt(0)
	v_mfma_f32_16x16x32_bf16 v[52:55], v[52:55], v[128:131], v[60:63]
	v_mfma_f32_16x16x32_bf16 v[40:43], v[44:47], v[40:43], v[64:67]
	v_mfma_f32_16x16x32_bf16 v[48:51], v[44:47], v[48:51], v[68:71]
	v_mfma_f32_16x16x32_bf16 v[60:63], v[44:47], v[76:79], v[72:75]
	v_mfma_f32_16x16x32_bf16 v[44:47], v[44:47], v[128:131], v[56:59]
	ds_read_b128 v[24:27], v80 offset:128
	ds_read_b128 v[32:35], v80 offset:4480
	s_nop 0
	ds_read_b128 v[56:59], v80 offset:8832
	ds_read_b128 v[64:67], v80 offset:13184
	s_waitcnt lgkmcnt(3)
	v_mfma_f32_16x16x32_bf16 v[68:71], v[36:39], v[24:27], v[116:119]
	s_waitcnt lgkmcnt(2)
	v_mfma_f32_16x16x32_bf16 v[72:75], v[36:39], v[32:35], v[120:123]
	v_mfma_f32_16x16x32_bf16 v[24:27], v[28:31], v[24:27], v[40:43]
	v_mfma_f32_16x16x32_bf16 v[32:35], v[28:31], v[32:35], v[48:51]
	s_waitcnt lgkmcnt(1)
	v_mfma_f32_16x16x32_bf16 v[40:43], v[28:31], v[56:59], v[60:63]
	s_waitcnt lgkmcnt(0)
	v_mfma_f32_16x16x32_bf16 v[28:31], v[28:31], v[64:67], v[44:47]
	ds_read_b128 v[8:11], v80 offset:192
	ds_read_b128 v[16:19], v80 offset:4544
	s_nop 0
	ds_read_b128 v[44:47], v80 offset:8896
	ds_read_b128 v[48:51], v80 offset:13248
	v_mfma_f32_16x16x32_bf16 v[76:79], v[36:39], v[56:59], v[124:127]
	v_mfma_f32_16x16x32_bf16 v[36:39], v[36:39], v[64:67], v[52:55]
	s_waitcnt lgkmcnt(3)
	v_mfma_f32_16x16x32_bf16 v[52:55], v[20:23], v[8:11], v[68:71]
	s_waitcnt lgkmcnt(2)
	v_mfma_f32_16x16x32_bf16 v[56:59], v[20:23], v[16:19], v[72:75]
	v_mfma_f32_16x16x32_bf16 v[8:11], v[12:15], v[8:11], v[24:27]
	v_mfma_f32_16x16x32_bf16 v[16:19], v[12:15], v[16:19], v[32:35]
	s_waitcnt lgkmcnt(1)
	v_mfma_f32_16x16x32_bf16 v[24:27], v[12:15], v[44:47], v[40:43]
	s_nop 1
	v_add_f32_e32 v32, v4, v52
	s_waitcnt lgkmcnt(0)
	v_mfma_f32_16x16x32_bf16 v[12:15], v[12:15], v[48:51], v[28:31]
	s_nop 2
	v_add_u32_e32 v28, s0, v104
	v_or_b32_e32 v28, v28, v105
	s_add_u32 s0, s22, s94
	v_ashrrev_i32_e32 v29, 31, v28
	s_addc_u32 s1, s23, 0
	v_lshlrev_b64 v[30:31], 11, v[28:29]
	v_lshlrev_b32_e32 v29, 16, v115
	v_lshl_add_u64 v[30:31], s[0:1], 0, v[30:31]
	v_mul_f32_e32 v29, v32, v29
	v_mfma_f32_16x16x32_bf16 v[60:63], v[20:23], v[44:47], v[76:79]
	v_cvt_pk_bf16_f32 v29, v29, s0
	v_lshl_add_u64 v[30:31], v[30:31], 0, v[200:201]
	global_store_short v[30:31], v29, off offset:512
	v_lshlrev_b32_e32 v29, 16, v114
	v_add_f32_e32 v32, v4, v56
	v_mul_f32_e32 v29, v32, v29
	v_mfma_f32_16x16x32_bf16 v[20:23], v[20:23], v[48:51], v[36:39]
	v_cvt_pk_bf16_f32 v29, v29, s0
	global_store_short v[30:31], v29, off offset:544
	v_lshlrev_b32_e32 v29, 16, v113
	v_add_f32_e32 v32, v4, v60
	v_mul_f32_e32 v29, v32, v29
	v_cvt_pk_bf16_f32 v29, v29, s0
	global_store_short v[30:31], v29, off offset:576
	v_lshlrev_b32_e32 v29, 16, v112
	v_add_f32_e32 v4, v4, v20
	v_mul_f32_e32 v4, v4, v29
	v_cvt_pk_bf16_f32 v4, v4, s0
	global_store_short v[30:31], v4, off offset:608
	v_or_b32_e32 v30, 1, v28
	v_ashrrev_i32_e32 v31, 31, v30
	v_lshlrev_b64 v[30:31], 11, v[30:31]
	v_lshlrev_b32_e32 v4, 16, v111
	v_add_f32_e32 v20, v5, v53
	v_lshl_add_u64 v[30:31], s[0:1], 0, v[30:31]
	v_mul_f32_e32 v4, v20, v4
	v_cvt_pk_bf16_f32 v4, v4, s0
	v_lshl_add_u64 v[30:31], v[30:31], 0, v[200:201]
	global_store_short v[30:31], v4, off offset:512
	v_lshlrev_b32_e32 v4, 16, v110
	v_add_f32_e32 v20, v5, v57
	v_mul_f32_e32 v4, v20, v4
	v_cvt_pk_bf16_f32 v4, v4, s0
	global_store_short v[30:31], v4, off offset:544
	v_lshlrev_b32_e32 v4, 16, v109
	v_add_f32_e32 v20, v5, v61
	v_mul_f32_e32 v4, v20, v4
	v_cvt_pk_bf16_f32 v4, v4, s0
	global_store_short v[30:31], v4, off offset:576
	v_lshlrev_b32_e32 v4, 16, v108
	v_add_f32_e32 v5, v5, v21
	v_mul_f32_e32 v4, v5, v4
	v_cvt_pk_bf16_f32 v4, v4, s0
	global_store_short v[30:31], v4, off offset:608
	v_or_b32_e32 v4, 2, v28
	v_ashrrev_i32_e32 v5, 31, v4
	v_lshlrev_b64 v[4:5], 11, v[4:5]
	v_lshlrev_b32_e32 v20, 16, v107
	v_add_f32_e32 v21, v6, v54
	v_lshl_add_u64 v[4:5], s[0:1], 0, v[4:5]
	v_mul_f32_e32 v20, v21, v20
	v_cvt_pk_bf16_f32 v20, v20, s0
	v_lshl_add_u64 v[4:5], v[4:5], 0, v[200:201]
	global_store_short v[4:5], v20, off offset:512
	v_lshlrev_b32_e32 v20, 16, v106
	v_add_f32_e32 v21, v6, v58
	v_mul_f32_e32 v20, v21, v20
	v_cvt_pk_bf16_f32 v20, v20, s0
	global_store_short v[4:5], v20, off offset:544
	v_lshlrev_b32_e32 v20, 16, v103
	v_add_f32_e32 v21, v6, v62
	v_mul_f32_e32 v20, v21, v20
	v_cvt_pk_bf16_f32 v20, v20, s0
	global_store_short v[4:5], v20, off offset:576
	v_lshlrev_b32_e32 v20, 16, v102
	v_add_f32_e32 v6, v6, v22
	v_mul_f32_e32 v6, v6, v20
	v_cvt_pk_bf16_f32 v6, v6, s0
	global_store_short v[4:5], v6, off offset:608
	v_or_b32_e32 v4, 3, v28
	v_ashrrev_i32_e32 v5, 31, v4
	v_lshlrev_b64 v[4:5], 11, v[4:5]
	v_lshlrev_b32_e32 v6, 16, v101
	v_add_f32_e32 v20, v7, v55
	v_lshl_add_u64 v[4:5], s[0:1], 0, v[4:5]
	v_mul_f32_e32 v6, v20, v6
	v_cvt_pk_bf16_f32 v6, v6, s0
	v_lshl_add_u64 v[4:5], v[4:5], 0, v[200:201]
	global_store_short v[4:5], v6, off offset:512
	v_lshlrev_b32_e32 v6, 16, v100
	v_add_f32_e32 v20, v7, v59
	v_mul_f32_e32 v6, v20, v6
	v_cvt_pk_bf16_f32 v6, v6, s0
	global_store_short v[4:5], v6, off offset:544
	v_lshlrev_b32_e32 v6, 16, v99
	v_add_f32_e32 v20, v7, v63
	v_mul_f32_e32 v6, v20, v6
	v_cvt_pk_bf16_f32 v6, v6, s0
	global_store_short v[4:5], v6, off offset:576
	v_lshlrev_b32_e32 v6, 16, v98
	v_add_f32_e32 v7, v7, v23
	v_mul_f32_e32 v6, v7, v6
	v_cvt_pk_bf16_f32 v6, v6, s0
	global_store_short v[4:5], v6, off offset:608
	v_or_b32_e32 v4, 16, v28
	v_ashrrev_i32_e32 v5, 31, v4
	v_lshlrev_b64 v[4:5], 11, v[4:5]
	v_lshlrev_b32_e32 v6, 16, v97
	v_add_f32_e32 v7, v0, v8
	v_lshl_add_u64 v[4:5], s[0:1], 0, v[4:5]
	v_mul_f32_e32 v6, v7, v6
	v_cvt_pk_bf16_f32 v6, v6, s0
	v_lshl_add_u64 v[4:5], v[4:5], 0, v[200:201]
	global_store_short v[4:5], v6, off offset:512
	v_lshlrev_b32_e32 v6, 16, v96
	v_add_f32_e32 v7, v0, v16
	v_mul_f32_e32 v6, v7, v6
	v_cvt_pk_bf16_f32 v6, v6, s0
	global_store_short v[4:5], v6, off offset:544
	v_lshlrev_b32_e32 v6, 16, v95
	v_add_f32_e32 v7, v0, v24
	v_mul_f32_e32 v6, v7, v6
	v_cvt_pk_bf16_f32 v6, v6, s0
	global_store_short v[4:5], v6, off offset:576
	v_lshlrev_b32_e32 v6, 16, v94
	v_add_f32_e32 v0, v0, v12
	v_mul_f32_e32 v0, v0, v6
	v_cvt_pk_bf16_f32 v0, v0, s0
	global_store_short v[4:5], v0, off offset:608
	v_or_b32_e32 v4, 17, v28
	v_ashrrev_i32_e32 v5, 31, v4
	v_lshlrev_b64 v[4:5], 11, v[4:5]
	v_lshlrev_b32_e32 v0, 16, v93
	v_add_f32_e32 v6, v1, v9
	v_lshl_add_u64 v[4:5], s[0:1], 0, v[4:5]
	v_mul_f32_e32 v0, v6, v0
	v_cvt_pk_bf16_f32 v0, v0, s0
	v_lshl_add_u64 v[4:5], v[4:5], 0, v[200:201]
	global_store_short v[4:5], v0, off offset:512
	v_lshlrev_b32_e32 v0, 16, v92
	v_add_f32_e32 v6, v1, v17
	v_mul_f32_e32 v0, v6, v0
	v_cvt_pk_bf16_f32 v0, v0, s0
	global_store_short v[4:5], v0, off offset:544
	v_lshlrev_b32_e32 v0, 16, v91
	v_add_f32_e32 v6, v1, v25
	v_mul_f32_e32 v0, v6, v0
	v_cvt_pk_bf16_f32 v0, v0, s0
	global_store_short v[4:5], v0, off offset:576
	v_lshlrev_b32_e32 v0, 16, v90
	v_add_f32_e32 v1, v1, v13
	v_mul_f32_e32 v0, v1, v0
	v_cvt_pk_bf16_f32 v0, v0, s0
	global_store_short v[4:5], v0, off offset:608
	v_or_b32_e32 v0, 18, v28
	v_ashrrev_i32_e32 v1, 31, v0
	v_lshlrev_b64 v[0:1], 11, v[0:1]
	v_lshlrev_b32_e32 v4, 16, v89
	v_add_f32_e32 v5, v2, v10
	v_lshl_add_u64 v[0:1], s[0:1], 0, v[0:1]
	v_mul_f32_e32 v4, v5, v4
	v_cvt_pk_bf16_f32 v4, v4, s0
	v_lshl_add_u64 v[0:1], v[0:1], 0, v[200:201]
	global_store_short v[0:1], v4, off offset:512
	v_lshlrev_b32_e32 v4, 16, v88
	v_add_f32_e32 v5, v2, v18
	v_mul_f32_e32 v4, v5, v4
	v_cvt_pk_bf16_f32 v4, v4, s0
	global_store_short v[0:1], v4, off offset:544
	v_lshlrev_b32_e32 v4, 16, v87
	v_add_f32_e32 v5, v2, v26
	v_mul_f32_e32 v4, v5, v4
	v_cvt_pk_bf16_f32 v4, v4, s0
	global_store_short v[0:1], v4, off offset:576
	v_lshlrev_b32_e32 v4, 16, v86
	v_add_f32_e32 v2, v2, v14
	v_mul_f32_e32 v2, v2, v4
	v_cvt_pk_bf16_f32 v2, v2, s0
	global_store_short v[0:1], v2, off offset:608
	v_or_b32_e32 v0, 19, v28
	v_ashrrev_i32_e32 v1, 31, v0
	v_lshlrev_b64 v[0:1], 11, v[0:1]
	v_lshlrev_b32_e32 v2, 16, v85
	v_add_f32_e32 v4, v3, v11
	v_lshl_add_u64 v[0:1], s[0:1], 0, v[0:1]
	v_mul_f32_e32 v2, v4, v2
	v_cvt_pk_bf16_f32 v2, v2, s0
	v_lshl_add_u64 v[0:1], v[0:1], 0, v[200:201]
	global_store_short v[0:1], v2, off offset:512
	v_lshlrev_b32_e32 v2, 16, v84
	v_add_f32_e32 v4, v3, v19
	v_mul_f32_e32 v2, v4, v2
	v_cvt_pk_bf16_f32 v2, v2, s0
	global_store_short v[0:1], v2, off offset:544
	v_lshlrev_b32_e32 v2, 16, v83
	v_add_f32_e32 v4, v3, v27
	v_mul_f32_e32 v2, v4, v2
	v_cvt_pk_bf16_f32 v2, v2, s0
	global_store_short v[0:1], v2, off offset:576
	v_lshlrev_b32_e32 v2, 16, v82
	v_add_f32_e32 v3, v3, v15
	v_mul_f32_e32 v2, v3, v2
	v_cvt_pk_bf16_f32 v2, v2, s0
	global_store_short v[0:1], v2, off offset:608
	v_mov_b32_e32 v82, v229
	s_waitcnt lgkmcnt(0)
	s_barrier
	v_mov_b32_e32 v3, v201
	v_ashrrev_i32_e32 v88, 6, v82
	v_add_u32_e32 v0, s75, v88
	v_ashrrev_i32_e32 v1, 31, v0
	v_lshlrev_b64 v[0:1], 13, v[0:1]
	v_and_b32_e32 v87, 15, v82
	v_lshl_add_u64 v[0:1], s[60:61], 0, v[0:1]
	v_and_b32_e32 v200, 48, v82
	v_lshl_add_u64 v[0:1], v[0:1], 0, v[200:201]
	v_lshlrev_b32_e32 v2, 7, v87
	v_or_b32_e32 v12, 0x1000, v2
	v_mov_b32_e32 v13, v201
	v_or_b32_e32 v14, 0x1800, v2
	v_mov_b32_e32 v15, v201
	v_lshl_add_u64 v[32:33], v[0:1], 0, 64
	v_lshl_add_u64 v[8:9], v[0:1], 0, v[2:3]
	v_lshl_add_u64 v[4:5], v[0:1], 0, v[12:13]
	v_lshl_add_u64 v[2:3], v[0:1], 0, v[14:15]
	v_lshl_add_u64 v[0:1], v[32:33], 0, v[12:13]
	v_lshl_add_u64 v[12:13], v[32:33], 0, v[14:15]
	v_and_b32_e32 v32, 0xffffffc0, v82
	v_add_u32_e32 v32, s76, v32
	v_or_b32_e32 v32, v32, v87
	v_ashrrev_i32_e32 v33, 31, v32
	v_lshl_add_u64 v[32:33], v[32:33], 2, s[46:47]
	global_load_dwordx4 v[20:23], v[8:9], off
	global_load_dwordx4 v[16:19], v[8:9], off offset:2048
	global_load_dwordx4 v[24:27], v[4:5], off
	global_load_dwordx4 v[28:31], v[2:3], off
	s_nop 0
	global_load_dwordx4 v[4:7], v[8:9], off offset:64
	s_nop 0
	global_load_dwordx4 v[8:11], v[8:9], off offset:2112
	s_cmpk_lt_i32 s2, 0x80
	global_load_dwordx4 v[0:3], v[0:1], off
	s_mov_b32 s0, 0x7ffffc00
	global_load_dwordx4 v[12:15], v[12:13], off
	s_nop 0
	global_load_dword v86, v[32:33], off
	global_load_dword v85, v[32:33], off offset:64
	global_load_dword v84, v[32:33], off offset:128
	global_load_dword v83, v[32:33], off offset:192
	s_cselect_b32 s0, 0xffffff00, s0
	s_movk_i32 s1, 0x400
	s_cselect_b32 s40, 0x100, s1
	s_and_b32 s28, s0, s3
	v_add_u32_e32 v76, s3, v88
	v_and_b32_e32 v34, 63, v82
	v_add_u32_e32 v33, -8, v76
	s_add_i32 s29, s28, s40
	v_lshlrev_b32_e32 v89, 2, v34
	v_cmp_le_i32_e32 vcc, s28, v33
	v_cmp_gt_i32_e64 s[0:1], s29, v33
	s_and_b64 s[38:39], vcc, s[0:1]
	v_mov_b32_e32 v32, 0
	v_lshlrev_b32_e32 v80, 1, v89
	v_mov_b32_e32 v81, v201
	s_mov_b32 s94, 0x800000
	s_mov_b64 s[0:1], exec
	v_add_u32_e32 v90, -8, v76
	v_cmp_le_i32_e32 vcc, s28, v90
	v_cmp_gt_i32_e64 s[38:39], s29, v90
	v_mov_b32_e32 v96, 0
	v_mov_b32_e32 v97, 0
	v_mov_b64_e32 v[92:93], s[20:21]
	s_nop 1
	s_and_b64 s[38:39], vcc, s[38:39]
	s_and_b64 exec, s[0:1], s[38:39]
	s_cbranch_execz .Lpool_skip0
	v_mad_i64_i32 v[92:93], vcc, v90, s92, v[92:93]
	v_lshl_add_u64 v[92:93], v[92:93], 0, v[80:81]
	global_load_dwordx2 v[96:97], v[92:93], off offset:2048
.Lpool_skip0:
	s_mov_b64 exec, s[0:1]
	v_add_u32_e32 v90, -4, v76
	v_cmp_le_i32_e32 vcc, s28, v90
	v_cmp_gt_i32_e64 s[38:39], s29, v90
	v_mov_b32_e32 v98, 0
	v_mov_b32_e32 v99, 0
	v_mov_b64_e32 v[92:93], s[20:21]
	s_nop 1
	s_and_b64 s[38:39], vcc, s[38:39]
	s_and_b64 exec, s[0:1], s[38:39]
	s_cbranch_execz .Lpool_skip1
	v_mad_i64_i32 v[92:93], vcc, v90, s92, v[92:93]
	v_lshl_add_u64 v[92:93], v[92:93], 0, v[80:81]
	global_load_dwordx2 v[98:99], v[92:93], off offset:2048
.Lpool_skip1:
	s_mov_b64 exec, s[0:1]
	v_mov_b32_e32 v90, v76
	v_cmp_le_i32_e32 vcc, s28, v90
	v_cmp_gt_i32_e64 s[38:39], s29, v90
	v_mov_b32_e32 v100, 0
	v_mov_b32_e32 v101, 0
	v_mov_b64_e32 v[92:93], s[20:21]
	s_nop 1
	s_and_b64 s[38:39], vcc, s[38:39]
	s_and_b64 exec, s[0:1], s[38:39]
	s_cbranch_execz .Lpool_skip2
	v_mad_i64_i32 v[92:93], vcc, v90, s92, v[92:93]
	v_lshl_add_u64 v[92:93], v[92:93], 0, v[80:81]
	global_load_dwordx2 v[100:101], v[92:93], off offset:2048
.Lpool_skip2:
	s_mov_b64 exec, s[0:1]
	v_add_u32_e32 v90, 4, v76
	v_cmp_le_i32_e32 vcc, s28, v90
	v_cmp_gt_i32_e64 s[38:39], s29, v90
	v_mov_b32_e32 v102, 0
	v_mov_b32_e32 v103, 0
	v_mov_b64_e32 v[92:93], s[20:21]
	s_nop 1
	s_and_b64 s[38:39], vcc, s[38:39]
	s_and_b64 exec, s[0:1], s[38:39]
	s_cbranch_execz .Lpool_skip3
	v_mad_i64_i32 v[92:93], vcc, v90, s92, v[92:93]
	v_lshl_add_u64 v[92:93], v[92:93], 0, v[80:81]
	global_load_dwordx2 v[102:103], v[92:93], off offset:2048
.Lpool_skip3:
	s_mov_b64 exec, s[0:1]
	v_add_u32_e32 v90, 8, v76
	v_cmp_le_i32_e32 vcc, s28, v90
	v_cmp_gt_i32_e64 s[38:39], s29, v90
	v_mov_b32_e32 v104, 0
	v_mov_b32_e32 v105, 0
	v_mov_b64_e32 v[92:93], s[20:21]
	s_nop 1
	s_and_b64 s[38:39], vcc, s[38:39]
	s_and_b64 exec, s[0:1], s[38:39]
	s_cbranch_execz .Lpool_skip4
	v_mad_i64_i32 v[92:93], vcc, v90, s92, v[92:93]
	v_lshl_add_u64 v[92:93], v[92:93], 0, v[80:81]
	global_load_dwordx2 v[104:105], v[92:93], off offset:2048
.Lpool_skip4:
	s_mov_b64 exec, s[0:1]
	v_add_u32_e32 v90, 12, v76
	v_cmp_le_i32_e32 vcc, s28, v90
	v_cmp_gt_i32_e64 s[38:39], s29, v90
	v_mov_b32_e32 v106, 0
	v_mov_b32_e32 v107, 0
	v_mov_b64_e32 v[92:93], s[20:21]
	s_nop 1
	s_and_b64 s[38:39], vcc, s[38:39]
	s_and_b64 exec, s[0:1], s[38:39]
	s_cbranch_execz .Lpool_skip5
	v_mad_i64_i32 v[92:93], vcc, v90, s92, v[92:93]
	v_lshl_add_u64 v[92:93], v[92:93], 0, v[80:81]
	global_load_dwordx2 v[106:107], v[92:93], off offset:2048
.Lpool_skip5:
	s_mov_b64 exec, s[0:1]
	v_add_u32_e32 v90, 16, v76
	v_cmp_le_i32_e32 vcc, s28, v90
	v_cmp_gt_i32_e64 s[38:39], s29, v90
	v_mov_b32_e32 v108, 0
	v_mov_b32_e32 v109, 0
	v_mov_b64_e32 v[92:93], s[20:21]
	s_nop 1
	s_and_b64 s[38:39], vcc, s[38:39]
	s_and_b64 exec, s[0:1], s[38:39]
	s_cbranch_execz .Lpool_skip6
	v_mad_i64_i32 v[92:93], vcc, v90, s92, v[92:93]
	v_lshl_add_u64 v[92:93], v[92:93], 0, v[80:81]
	global_load_dwordx2 v[108:109], v[92:93], off offset:2048
.Lpool_skip6:
	s_mov_b64 exec, s[0:1]
	v_add_u32_e32 v90, 20, v76
	v_cmp_le_i32_e32 vcc, s28, v90
	v_cmp_gt_i32_e64 s[38:39], s29, v90
	v_mov_b32_e32 v110, 0
	v_mov_b32_e32 v111, 0
	v_mov_b64_e32 v[92:93], s[20:21]
	s_nop 1
	s_and_b64 s[38:39], vcc, s[38:39]
	s_and_b64 exec, s[0:1], s[38:39]
	s_cbranch_execz .Lpool_skip7
	v_mad_i64_i32 v[92:93], vcc, v90, s92, v[92:93]
	v_lshl_add_u64 v[92:93], v[92:93], 0, v[80:81]
	global_load_dwordx2 v[110:111], v[92:93], off offset:2048
.Lpool_skip7:
	s_mov_b64 exec, s[0:1]
	v_add_u32_e32 v90, 24, v76
	v_cmp_le_i32_e32 vcc, s28, v90
	v_cmp_gt_i32_e64 s[38:39], s29, v90
	v_mov_b32_e32 v112, 0
	v_mov_b32_e32 v113, 0
	v_mov_b64_e32 v[92:93], s[20:21]
	s_nop 1
	s_and_b64 s[38:39], vcc, s[38:39]
	s_and_b64 exec, s[0:1], s[38:39]
	s_cbranch_execz .Lpool_skip8
	v_mad_i64_i32 v[92:93], vcc, v90, s92, v[92:93]
	v_lshl_add_u64 v[92:93], v[92:93], 0, v[80:81]
	global_load_dwordx2 v[112:113], v[92:93], off offset:2048
.Lpool_skip8:
	s_mov_b64 exec, s[0:1]
	v_add_u32_e32 v90, 28, v76
	v_cmp_le_i32_e32 vcc, s28, v90
	v_cmp_gt_i32_e64 s[38:39], s29, v90
	v_mov_b32_e32 v114, 0
	v_mov_b32_e32 v115, 0
	v_mov_b64_e32 v[92:93], s[20:21]
	s_nop 1
	s_and_b64 s[38:39], vcc, s[38:39]
	s_and_b64 exec, s[0:1], s[38:39]
	s_cbranch_execz .Lpool_skip9
	v_mad_i64_i32 v[92:93], vcc, v90, s92, v[92:93]
	v_lshl_add_u64 v[92:93], v[92:93], 0, v[80:81]
	global_load_dwordx2 v[114:115], v[92:93], off offset:2048
.Lpool_skip9:
	s_mov_b64 exec, s[0:1]
	v_add_u32_e32 v90, 32, v76
	v_cmp_le_i32_e32 vcc, s28, v90
	v_cmp_gt_i32_e64 s[38:39], s29, v90
	v_mov_b32_e32 v116, 0
	v_mov_b32_e32 v117, 0
	v_mov_b64_e32 v[92:93], s[20:21]
	s_nop 1
	s_and_b64 s[38:39], vcc, s[38:39]
	s_and_b64 exec, s[0:1], s[38:39]
	s_cbranch_execz .Lpool_skip10
	v_mad_i64_i32 v[92:93], vcc, v90, s92, v[92:93]
	v_lshl_add_u64 v[92:93], v[92:93], 0, v[80:81]
	global_load_dwordx2 v[116:117], v[92:93], off offset:2048
.Lpool_skip10:
	s_mov_b64 exec, s[0:1]
	v_add_u32_e32 v90, 36, v76
	v_cmp_le_i32_e32 vcc, s28, v90
	v_cmp_gt_i32_e64 s[38:39], s29, v90
	v_mov_b32_e32 v118, 0
	v_mov_b32_e32 v119, 0
	v_mov_b64_e32 v[92:93], s[20:21]
	s_nop 1
	s_and_b64 s[38:39], vcc, s[38:39]
	s_and_b64 exec, s[0:1], s[38:39]
	s_cbranch_execz .Lpool_skip11
	v_mad_i64_i32 v[92:93], vcc, v90, s92, v[92:93]
	v_lshl_add_u64 v[92:93], v[92:93], 0, v[80:81]
	global_load_dwordx2 v[118:119], v[92:93], off offset:2048
.Lpool_skip11:
	s_mov_b64 exec, s[0:1]
	s_waitcnt vmcnt(0)
	v_lshlrev_b32_e32 v36, 16, v96
	v_and_b32_e32 v37, 0xffff0000, v96
	v_lshlrev_b32_e32 v38, 16, v97
	v_and_b32_e32 v39, 0xffff0000, v97
	v_lshlrev_b32_e32 v40, 16, v98
	v_and_b32_e32 v41, 0xffff0000, v98
	v_lshlrev_b32_e32 v42, 16, v99
	v_and_b32_e32 v43, 0xffff0000, v99
	v_lshlrev_b32_e32 v32, 16, v100
	v_and_b32_e32 v33, 0xffff0000, v100
	v_lshlrev_b32_e32 v34, 16, v101
	v_and_b32_e32 v35, 0xffff0000, v101
	v_lshlrev_b32_e32 v48, 16, v102
	v_and_b32_e32 v49, 0xffff0000, v102
	v_lshlrev_b32_e32 v50, 16, v103
	v_and_b32_e32 v51, 0xffff0000, v103
	v_lshlrev_b32_e32 v44, 16, v104
	v_and_b32_e32 v45, 0xffff0000, v104
	v_lshlrev_b32_e32 v46, 16, v105
	v_and_b32_e32 v47, 0xffff0000, v105
	v_lshlrev_b32_e32 v56, 16, v106
	v_and_b32_e32 v57, 0xffff0000, v106
	v_lshlrev_b32_e32 v58, 16, v107
	v_and_b32_e32 v59, 0xffff0000, v107
	v_lshlrev_b32_e32 v52, 16, v108
	v_and_b32_e32 v53, 0xffff0000, v108
	v_lshlrev_b32_e32 v54, 16, v109
	v_and_b32_e32 v55, 0xffff0000, v109
	v_lshlrev_b32_e32 v64, 16, v110
	v_and_b32_e32 v65, 0xffff0000, v110
	v_lshlrev_b32_e32 v66, 16, v111
	v_and_b32_e32 v67, 0xffff0000, v111
	v_lshlrev_b32_e32 v60, 16, v112
	v_and_b32_e32 v61, 0xffff0000, v112
	v_lshlrev_b32_e32 v62, 16, v113
	v_and_b32_e32 v63, 0xffff0000, v113
	v_lshlrev_b32_e32 v72, 16, v114
	v_and_b32_e32 v73, 0xffff0000, v114
	v_lshlrev_b32_e32 v74, 16, v115
	v_and_b32_e32 v75, 0xffff0000, v115
	v_lshlrev_b32_e32 v68, 16, v116
	v_and_b32_e32 v69, 0xffff0000, v116
	v_lshlrev_b32_e32 v70, 16, v117
	v_and_b32_e32 v71, 0xffff0000, v117
	v_lshlrev_b32_e32 v76, 16, v118
	v_and_b32_e32 v77, 0xffff0000, v118
	v_lshlrev_b32_e32 v78, 16, v119
	v_and_b32_e32 v79, 0xffff0000, v119

.LBB0_443:
	v_mov_b32_e32 v122, v229
	v_readlane_b32 s40, v254, 30
	v_add_u32_e32 v0, s81, v122
	s_waitcnt lgkmcnt(0)
	v_ashrrev_i32_e32 v1, 31, v0
	v_readlane_b32 s46, v254, 36
	v_readlane_b32 s47, v254, 37
	v_and_b32_e32 v123, 63, v122
	v_readlane_b32 s48, v254, 38
	v_lshl_add_u64 v[2:3], v[0:1], 2, s[46:47]
	global_load_dword v108, v[2:3], off
	v_add_u32_e32 v2, 0x100, v0
	v_ashrrev_i32_e32 v3, 31, v2
	v_lshl_add_u64 v[2:3], v[2:3], 2, s[46:47]
	global_load_dword v107, v[2:3], off
	v_add_u32_e32 v2, 0x200, v0
	v_ashrrev_i32_e32 v3, 31, v2
	v_lshl_add_u64 v[2:3], v[2:3], 2, s[46:47]
	global_load_dword v106, v[2:3], off
	v_add_u32_e32 v2, 0x300, v0
	v_ashrrev_i32_e32 v3, 31, v2
	v_lshl_add_u64 v[2:3], v[2:3], 2, s[46:47]
	global_load_dword v103, v[2:3], off
	v_add_u32_e32 v2, 0x400, v0
	v_ashrrev_i32_e32 v3, 31, v2
	v_lshl_add_u64 v[2:3], v[2:3], 2, s[46:47]
	global_load_dword v101, v[2:3], off
	v_add_u32_e32 v2, 0x500, v0
	v_ashrrev_i32_e32 v3, 31, v2
	v_lshl_add_u64 v[2:3], v[2:3], 2, s[46:47]
	global_load_dword v100, v[2:3], off
	v_add_u32_e32 v2, 0x600, v0
	v_ashrrev_i32_e32 v3, 31, v2
	v_lshl_add_u64 v[2:3], v[2:3], 2, s[46:47]
	global_load_dword v99, v[2:3], off
	v_add_u32_e32 v2, 0x700, v0
	v_ashrrev_i32_e32 v3, 31, v2
	v_lshl_add_u64 v[2:3], v[2:3], 2, s[46:47]
	global_load_dword v98, v[2:3], off
	v_add_u32_e32 v2, 0x800, v0
	v_ashrrev_i32_e32 v3, 31, v2
	v_lshl_add_u64 v[2:3], v[2:3], 2, s[46:47]
	global_load_dword v97, v[2:3], off
	v_add_u32_e32 v2, 0x900, v0
	v_ashrrev_i32_e32 v3, 31, v2
	v_lshl_add_u64 v[2:3], v[2:3], 2, s[46:47]
	global_load_dword v96, v[2:3], off
	v_add_u32_e32 v2, 0xa00, v0
	v_ashrrev_i32_e32 v3, 31, v2
	v_lshl_add_u64 v[2:3], v[2:3], 2, s[46:47]
	global_load_dword v95, v[2:3], off
	v_add_u32_e32 v2, 0xb00, v0
	v_ashrrev_i32_e32 v3, 31, v2
	v_lshl_add_u64 v[2:3], v[2:3], 2, s[46:47]
	global_load_dword v94, v[2:3], off
	v_add_u32_e32 v2, 0xc00, v0
	v_ashrrev_i32_e32 v3, 31, v2
	v_lshl_add_u64 v[2:3], v[2:3], 2, s[46:47]
	global_load_dword v93, v[2:3], off
	v_add_u32_e32 v2, 0xd00, v0
	v_ashrrev_i32_e32 v3, 31, v2
	v_lshl_add_u64 v[2:3], v[2:3], 2, s[46:47]
	global_load_dword v92, v[2:3], off
	v_add_u32_e32 v2, 0xe00, v0
	v_ashrrev_i32_e32 v3, 31, v2
	v_lshl_add_u64 v[2:3], v[2:3], 2, s[46:47]
	global_load_dword v91, v[2:3], off
	v_add_u32_e32 v2, 0xf00, v0
	v_ashrrev_i32_e32 v3, 31, v2
	v_lshl_add_u64 v[2:3], v[2:3], 2, s[46:47]
	global_load_dword v90, v[2:3], off
	v_add_u32_e32 v2, 0x1000, v0
	v_ashrrev_i32_e32 v3, 31, v2
	v_lshl_add_u64 v[2:3], v[2:3], 2, s[46:47]
	global_load_dword v89, v[2:3], off
	v_add_u32_e32 v2, 0x1100, v0
	v_ashrrev_i32_e32 v3, 31, v2
	v_lshl_add_u64 v[2:3], v[2:3], 2, s[46:47]
	global_load_dword v88, v[2:3], off
	v_add_u32_e32 v2, 0x1200, v0
	v_ashrrev_i32_e32 v3, 31, v2
	v_lshl_add_u64 v[2:3], v[2:3], 2, s[46:47]
	global_load_dword v87, v[2:3], off
	v_add_u32_e32 v2, 0x1300, v0
	v_ashrrev_i32_e32 v3, 31, v2
	v_lshl_add_u64 v[2:3], v[2:3], 2, s[46:47]
	global_load_dword v86, v[2:3], off
	v_add_u32_e32 v2, 0x1400, v0
	v_ashrrev_i32_e32 v3, 31, v2
	v_lshl_add_u64 v[2:3], v[2:3], 2, s[46:47]
	global_load_dword v85, v[2:3], off
	v_add_u32_e32 v2, 0x1500, v0
	v_ashrrev_i32_e32 v3, 31, v2
	v_lshl_add_u64 v[2:3], v[2:3], 2, s[46:47]
	global_load_dword v84, v[2:3], off
	v_add_u32_e32 v2, 0x1600, v0
	v_ashrrev_i32_e32 v3, 31, v2
	v_lshl_add_u64 v[2:3], v[2:3], 2, s[46:47]
	global_load_dword v83, v[2:3], off
	v_add_u32_e32 v2, 0x1700, v0
	v_ashrrev_i32_e32 v3, 31, v2
	v_lshl_add_u64 v[2:3], v[2:3], 2, s[46:47]
	global_load_dword v82, v[2:3], off
	v_add_u32_e32 v2, 0x1800, v0
	v_ashrrev_i32_e32 v3, 31, v2
	v_lshl_add_u64 v[2:3], v[2:3], 2, s[46:47]
	global_load_dword v81, v[2:3], off
	v_add_u32_e32 v2, 0x1900, v0
	v_ashrrev_i32_e32 v3, 31, v2
	v_lshl_add_u64 v[2:3], v[2:3], 2, s[46:47]
	global_load_dword v80, v[2:3], off
	v_add_u32_e32 v2, 0x1a00, v0
	v_ashrrev_i32_e32 v3, 31, v2
	v_lshl_add_u64 v[2:3], v[2:3], 2, s[46:47]
	global_load_dword v79, v[2:3], off
	v_add_u32_e32 v2, 0x1b00, v0
	v_ashrrev_i32_e32 v3, 31, v2
	v_lshl_add_u64 v[2:3], v[2:3], 2, s[46:47]
	global_load_dword v78, v[2:3], off
	v_add_u32_e32 v2, 0x1c00, v0
	v_ashrrev_i32_e32 v3, 31, v2
	v_lshl_add_u64 v[2:3], v[2:3], 2, s[46:47]
	global_load_dword v77, v[2:3], off
	v_add_u32_e32 v2, 0x1d00, v0
	v_add_u32_e32 v0, 0x1e00, v0
	v_ashrrev_i32_e32 v3, 31, v2
	v_ashrrev_i32_e32 v1, 31, v0
	v_lshl_add_u64 v[2:3], v[2:3], 2, s[46:47]
	v_lshl_add_u64 v[0:1], v[0:1], 2, s[46:47]
	global_load_dword v76, v[2:3], off
	global_load_dword v74, v[0:1], off
	v_add_u32_e32 v0, s76, v122
	v_readlane_b32 s49, v254, 39
	v_ashrrev_i32_e32 v1, 31, v0
	v_lshlrev_b32_e32 v4, 4, v123
	v_lshl_add_u64 v[0:1], v[0:1], 2, s[48:49]
	global_load_dword v75, v[0:1], off
	s_nop 0
	global_load_dwordx4 v[0:3], v4, s[82:83]
	s_nop 0
	global_load_dwordx4 v[4:7], v4, s[84:85]
	s_add_i32 s94, s33, s90
	s_cmpk_lt_i32 s94, 0x80
	s_mov_b32 s0, 0x7ffffc00
	s_cselect_b32 s1, 0xffffff00, s0
	s_movk_i32 s0, 0x400
	s_cselect_b32 s0, 0x100, s0
	s_lshl_b32 s2, s94, 5
	v_ashrrev_i32_e32 v124, 6, v122
	s_and_b32 s3, s1, s2
	s_waitcnt vmcnt(0)
	v_lshlrev_b32_e32 v104, 3, v123
	v_mov_b32_e32 v105, v201
	v_readlane_b32 s41, v254, 31
	v_lshlrev_b32_e32 v102, 2, v123
	s_add_i32 s29, s2, -15
	s_add_i32 s28, s3, s0
	v_lshl_add_u64 v[18:19], s[20:21], 0, v[104:105]
	v_cmp_gt_i32_e32 vcc, 62, v124
	v_mov_b32_e32 v8, 0
	v_mov_b32_e32 v10, 0
	v_mov_b32_e32 v11, 0
	v_mov_b32_e32 v12, 0
	v_mov_b32_e32 v13, 0
	v_mov_b32_e32 v109, 0
	v_mov_b32_e32 v110, 0
	v_mov_b32_e32 v111, 0
	v_mov_b32_e32 v112, 0
	v_readlane_b32 s42, v254, 32
	v_readlane_b32 s43, v254, 33
	v_readlane_b32 s44, v254, 34
	v_readlane_b32 s45, v254, 35
	v_readlane_b32 s50, v254, 40
	v_readlane_b32 s51, v254, 41
	v_readlane_b32 s52, v254, 42
	v_readlane_b32 s53, v254, 43
	v_readlane_b32 s54, v254, 44
	v_readlane_b32 s55, v254, 45
	s_mov_b64 s[96:97], exec
	v_lshlrev_b32_e32 v200, 1, v102
	v_add_u32_e32 v194, s29, v124
	v_cmp_le_i32_e64 s[0:1], s3, v194
	v_cmp_gt_i32_e64 s[72:73], s28, v194
	v_mov_b32_e32 v11, 0
	v_mov_b32_e32 v13, 0
	v_mov_b32_e32 v110, 0
	v_mov_b32_e32 v112, 0
	s_and_b64 s[0:1], s[0:1], s[72:73]
	s_and_b64 s[0:1], s[0:1], vcc
	s_and_b64 exec, s[96:97], s[0:1]
	s_cbranch_execz .Lglu_skip0
	v_mad_i64_i32 v[192:193], s[72:73], v194, s92, v[18:19]
	global_load_dword v11, v[192:193], off
	global_load_dword v13, v[192:193], off offset:4
	global_load_dword v110, v[192:193], off offset:512
	global_load_dword v112, v[192:193], off offset:516
.Lglu_skip0:
	s_mov_b64 exec, s[96:97]
	v_add_u32_e32 v105, 4, v124
	v_cmp_gt_i32_e64 s[38:39], 58, v124
	v_add_u32_e32 v194, s29, v105
	v_cmp_le_i32_e64 s[0:1], s3, v194
	v_cmp_gt_i32_e64 s[72:73], s28, v194
	v_mov_b32_e32 v9, 0
	v_mov_b32_e32 v17, 0
	v_mov_b32_e32 v115, 0
	v_mov_b32_e32 v117, 0
	s_and_b64 s[0:1], s[0:1], s[72:73]
	s_and_b64 s[0:1], s[0:1], s[38:39]
	s_and_b64 exec, s[96:97], s[0:1]
	s_cbranch_execz .Lglu_skip1
	v_mad_i64_i32 v[192:193], s[72:73], v194, s92, v[18:19]
	global_load_dword v9, v[192:193], off
	global_load_dword v17, v[192:193], off offset:4
	global_load_dword v115, v[192:193], off offset:512
	global_load_dword v117, v[192:193], off offset:516
.Lglu_skip1:
	s_mov_b64 exec, s[96:97]
	v_add_u32_e32 v113, 8, v124
	v_cmp_gt_i32_e64 s[40:41], 54, v124
	v_add_u32_e32 v194, s29, v113
	v_cmp_le_i32_e64 s[0:1], s3, v194
	v_cmp_gt_i32_e64 s[72:73], s28, v194
	v_mov_b32_e32 v21, 0
	v_mov_b32_e32 v23, 0
	v_mov_b32_e32 v120, 0
	v_mov_b32_e32 v125, 0
	s_and_b64 s[0:1], s[0:1], s[72:73]
	s_and_b64 s[0:1], s[0:1], s[40:41]
	s_and_b64 exec, s[96:97], s[0:1]
	s_cbranch_execz .Lglu_skip2
	v_mad_i64_i32 v[192:193], s[72:73], v194, s92, v[18:19]
	global_load_dword v21, v[192:193], off
	global_load_dword v23, v[192:193], off offset:4
	global_load_dword v120, v[192:193], off offset:512
	global_load_dword v125, v[192:193], off offset:516
.Lglu_skip2:
	s_mov_b64 exec, s[96:97]
	v_add_u32_e32 v118, 12, v124
	v_cmp_gt_i32_e64 s[42:43], 50, v124
	v_add_u32_e32 v194, s29, v118
	v_cmp_le_i32_e64 s[0:1], s3, v194
	v_cmp_gt_i32_e64 s[72:73], s28, v194
	v_mov_b32_e32 v15, 0
	v_mov_b32_e32 v27, 0
	v_mov_b32_e32 v128, 0
	v_mov_b32_e32 v130, 0
	s_and_b64 s[0:1], s[0:1], s[72:73]
	s_and_b64 s[0:1], s[0:1], s[42:43]
	s_and_b64 exec, s[96:97], s[0:1]
	s_cbranch_execz .Lglu_skip3
	v_mad_i64_i32 v[192:193], s[72:73], v194, s92, v[18:19]
	global_load_dword v15, v[192:193], off
	global_load_dword v27, v[192:193], off offset:4
	global_load_dword v128, v[192:193], off offset:512
	global_load_dword v130, v[192:193], off offset:516
.Lglu_skip3:
	s_mov_b64 exec, s[96:97]
	v_add_u32_e32 v126, 16, v124
	v_cmp_gt_i32_e64 s[44:45], 46, v124
	v_add_u32_e32 v194, s29, v126
	v_cmp_le_i32_e64 s[0:1], s3, v194
	v_cmp_gt_i32_e64 s[72:73], s28, v194
	v_mov_b32_e32 v29, 0
	v_mov_b32_e32 v31, 0
	v_mov_b32_e32 v133, 0
	v_mov_b32_e32 v135, 0
	s_and_b64 s[0:1], s[0:1], s[72:73]
	s_and_b64 s[0:1], s[0:1], s[44:45]
	s_and_b64 exec, s[96:97], s[0:1]
	s_cbranch_execz .Lglu_skip4
	v_mad_i64_i32 v[192:193], s[72:73], v194, s92, v[18:19]
	global_load_dword v29, v[192:193], off
	global_load_dword v31, v[192:193], off offset:4
	global_load_dword v133, v[192:193], off offset:512
	global_load_dword v135, v[192:193], off offset:516
.Lglu_skip4:
	s_mov_b64 exec, s[96:97]
	v_add_u32_e32 v131, 20, v124
	v_cmp_gt_i32_e64 s[46:47], 42, v124
	v_add_u32_e32 v194, s29, v131
	v_cmp_le_i32_e64 s[0:1], s3, v194
	v_cmp_gt_i32_e64 s[72:73], s28, v194
	v_mov_b32_e32 v25, 0
	v_mov_b32_e32 v35, 0
	v_mov_b32_e32 v138, 0
	v_mov_b32_e32 v140, 0
	s_and_b64 s[0:1], s[0:1], s[72:73]
	s_and_b64 s[0:1], s[0:1], s[46:47]
	s_and_b64 exec, s[96:97], s[0:1]
	s_cbranch_execz .Lglu_skip5
	v_mad_i64_i32 v[192:193], s[72:73], v194, s92, v[18:19]
	global_load_dword v25, v[192:193], off
	global_load_dword v35, v[192:193], off offset:4
	global_load_dword v138, v[192:193], off offset:512
	global_load_dword v140, v[192:193], off offset:516
.Lglu_skip5:
	s_mov_b64 exec, s[96:97]
	v_add_u32_e32 v136, 24, v124
	v_cmp_gt_i32_e64 s[48:49], 38, v124
	v_add_u32_e32 v194, s29, v136
	v_cmp_le_i32_e64 s[0:1], s3, v194
	v_cmp_gt_i32_e64 s[72:73], s28, v194
	v_mov_b32_e32 v37, 0
	v_mov_b32_e32 v39, 0
	v_mov_b32_e32 v143, 0
	v_mov_b32_e32 v145, 0
	s_and_b64 s[0:1], s[0:1], s[72:73]
	s_and_b64 s[0:1], s[0:1], s[48:49]
	s_and_b64 exec, s[96:97], s[0:1]
	s_cbranch_execz .Lglu_skip6
	v_mad_i64_i32 v[192:193], s[72:73], v194, s92, v[18:19]
	global_load_dword v37, v[192:193], off
	global_load_dword v39, v[192:193], off offset:4
	global_load_dword v143, v[192:193], off offset:512
	global_load_dword v145, v[192:193], off offset:516
.Lglu_skip6:
	s_mov_b64 exec, s[96:97]
	v_add_u32_e32 v141, 28, v124
	v_cmp_gt_i32_e64 s[50:51], 34, v124
	v_add_u32_e32 v194, s29, v141
	v_cmp_le_i32_e64 s[0:1], s3, v194
	v_cmp_gt_i32_e64 s[72:73], s28, v194
	v_mov_b32_e32 v33, 0
	v_mov_b32_e32 v43, 0
	v_mov_b32_e32 v148, 0
	v_mov_b32_e32 v150, 0
	s_and_b64 s[0:1], s[0:1], s[72:73]
	s_and_b64 s[0:1], s[0:1], s[50:51]
	s_and_b64 exec, s[96:97], s[0:1]
	s_cbranch_execz .Lglu_skip7
	v_mad_i64_i32 v[192:193], s[72:73], v194, s92, v[18:19]
	global_load_dword v33, v[192:193], off
	global_load_dword v43, v[192:193], off offset:4
	global_load_dword v148, v[192:193], off offset:512
	global_load_dword v150, v[192:193], off offset:516
.Lglu_skip7:
	s_mov_b64 exec, s[96:97]
	v_add_u32_e32 v146, 32, v124
	v_cmp_gt_i32_e64 s[52:53], 30, v124
	v_add_u32_e32 v194, s29, v146
	v_cmp_le_i32_e64 s[0:1], s3, v194
	v_cmp_gt_i32_e64 s[72:73], s28, v194
	v_mov_b32_e32 v45, 0
	v_mov_b32_e32 v47, 0
	v_mov_b32_e32 v153, 0
	v_mov_b32_e32 v155, 0
	s_and_b64 s[0:1], s[0:1], s[72:73]
	s_and_b64 s[0:1], s[0:1], s[52:53]
	s_and_b64 exec, s[96:97], s[0:1]
	s_cbranch_execz .Lglu_skip8
	v_mad_i64_i32 v[192:193], s[72:73], v194, s92, v[18:19]
	global_load_dword v45, v[192:193], off
	global_load_dword v47, v[192:193], off offset:4
	global_load_dword v153, v[192:193], off offset:512
	global_load_dword v155, v[192:193], off offset:516
.Lglu_skip8:
	s_mov_b64 exec, s[96:97]
	v_add_u32_e32 v151, 36, v124
	v_cmp_gt_i32_e64 s[54:55], 26, v124
	v_add_u32_e32 v194, s29, v151
	v_cmp_le_i32_e64 s[0:1], s3, v194
	v_cmp_gt_i32_e64 s[72:73], s28, v194
	v_mov_b32_e32 v41, 0
	v_mov_b32_e32 v51, 0
	v_mov_b32_e32 v158, 0
	v_mov_b32_e32 v160, 0
	s_and_b64 s[0:1], s[0:1], s[72:73]
	s_and_b64 s[0:1], s[0:1], s[54:55]
	s_and_b64 exec, s[96:97], s[0:1]
	s_cbranch_execz .Lglu_skip9
	v_mad_i64_i32 v[192:193], s[72:73], v194, s92, v[18:19]
	global_load_dword v41, v[192:193], off
	global_load_dword v51, v[192:193], off offset:4
	global_load_dword v158, v[192:193], off offset:512
	global_load_dword v160, v[192:193], off offset:516
.Lglu_skip9:
	s_mov_b64 exec, s[96:97]
	v_add_u32_e32 v156, 40, v124
	v_cmp_gt_i32_e64 s[56:57], 22, v124
	v_add_u32_e32 v194, s29, v156
	v_cmp_le_i32_e64 s[0:1], s3, v194
	v_cmp_gt_i32_e64 s[72:73], s28, v194
	v_mov_b32_e32 v53, 0
	v_mov_b32_e32 v55, 0
	v_mov_b32_e32 v163, 0
	v_mov_b32_e32 v165, 0
	s_and_b64 s[0:1], s[0:1], s[72:73]
	s_and_b64 s[0:1], s[0:1], s[56:57]
	s_and_b64 exec, s[96:97], s[0:1]
	s_cbranch_execz .Lglu_skip10
	v_mad_i64_i32 v[192:193], s[72:73], v194, s92, v[18:19]
	global_load_dword v53, v[192:193], off
	global_load_dword v55, v[192:193], off offset:4
	global_load_dword v163, v[192:193], off offset:512
	global_load_dword v165, v[192:193], off offset:516
.Lglu_skip10:
	s_mov_b64 exec, s[96:97]
	v_add_u32_e32 v161, 44, v124
	v_cmp_gt_i32_e64 s[58:59], 18, v124
	v_add_u32_e32 v194, s29, v161
	v_cmp_le_i32_e64 s[0:1], s3, v194
	v_cmp_gt_i32_e64 s[72:73], s28, v194
	v_mov_b32_e32 v49, 0
	v_mov_b32_e32 v59, 0
	v_mov_b32_e32 v168, 0
	v_mov_b32_e32 v170, 0
	s_and_b64 s[0:1], s[0:1], s[72:73]
	s_and_b64 s[0:1], s[0:1], s[58:59]
	s_and_b64 exec, s[96:97], s[0:1]
	s_cbranch_execz .Lglu_skip11
	v_mad_i64_i32 v[192:193], s[72:73], v194, s92, v[18:19]
	global_load_dword v49, v[192:193], off
	global_load_dword v59, v[192:193], off offset:4
	global_load_dword v168, v[192:193], off offset:512
	global_load_dword v170, v[192:193], off offset:516
.Lglu_skip11:
	s_mov_b64 exec, s[96:97]
	v_add_u32_e32 v166, 48, v124
	v_cmp_gt_i32_e64 s[60:61], 14, v124
	v_add_u32_e32 v194, s29, v166
	v_cmp_le_i32_e64 s[0:1], s3, v194
	v_cmp_gt_i32_e64 s[72:73], s28, v194
	v_mov_b32_e32 v61, 0
	v_mov_b32_e32 v63, 0
	v_mov_b32_e32 v173, 0
	v_mov_b32_e32 v175, 0
	s_and_b64 s[0:1], s[0:1], s[72:73]
	s_and_b64 s[0:1], s[0:1], s[60:61]
	s_and_b64 exec, s[96:97], s[0:1]
	s_cbranch_execz .Lglu_skip12
	v_mad_i64_i32 v[192:193], s[72:73], v194, s92, v[18:19]
	global_load_dword v61, v[192:193], off
	global_load_dword v63, v[192:193], off offset:4
	global_load_dword v173, v[192:193], off offset:512
	global_load_dword v175, v[192:193], off offset:516
.Lglu_skip12:
	s_mov_b64 exec, s[96:97]
	v_add_u32_e32 v171, 52, v124
	v_cmp_gt_i32_e64 s[62:63], 10, v124
	v_add_u32_e32 v194, s29, v171
	v_cmp_le_i32_e64 s[0:1], s3, v194
	v_cmp_gt_i32_e64 s[72:73], s28, v194
	v_mov_b32_e32 v57, 0
	v_mov_b32_e32 v67, 0
	v_mov_b32_e32 v178, 0
	v_mov_b32_e32 v180, 0
	s_and_b64 s[0:1], s[0:1], s[72:73]
	s_and_b64 s[0:1], s[0:1], s[62:63]
	s_and_b64 exec, s[96:97], s[0:1]
	s_cbranch_execz .Lglu_skip13
	v_mad_i64_i32 v[192:193], s[72:73], v194, s92, v[18:19]
	global_load_dword v57, v[192:193], off
	global_load_dword v67, v[192:193], off offset:4
	global_load_dword v178, v[192:193], off offset:512
	global_load_dword v180, v[192:193], off offset:516
.Lglu_skip13:
	s_mov_b64 exec, s[96:97]
	v_add_u32_e32 v176, 56, v124
	v_cmp_gt_i32_e64 s[64:65], 6, v124
	v_add_u32_e32 v194, s29, v176
	v_cmp_le_i32_e64 s[0:1], s3, v194
	v_cmp_gt_i32_e64 s[72:73], s28, v194
	v_mov_b32_e32 v69, 0
	v_mov_b32_e32 v71, 0
	v_mov_b32_e32 v183, 0
	v_mov_b32_e32 v185, 0
	s_and_b64 s[0:1], s[0:1], s[72:73]
	s_and_b64 s[0:1], s[0:1], s[64:65]
	s_and_b64 exec, s[96:97], s[0:1]
	s_cbranch_execz .Lglu_skip14
	v_mad_i64_i32 v[192:193], s[72:73], v194, s92, v[18:19]
	global_load_dword v69, v[192:193], off
	global_load_dword v71, v[192:193], off offset:4
	global_load_dword v183, v[192:193], off offset:512
	global_load_dword v185, v[192:193], off offset:516
.Lglu_skip14:
	s_mov_b64 exec, s[96:97]
	v_add_u32_e32 v181, 60, v124
	v_cmp_gt_i32_e64 s[66:67], 2, v124
	v_add_u32_e32 v194, s29, v181
	v_cmp_le_i32_e64 s[0:1], s3, v194
	v_cmp_gt_i32_e64 s[72:73], s28, v194
	v_mov_b32_e32 v65, 0
	v_mov_b32_e32 v73, 0
	v_mov_b32_e32 v187, 0
	v_mov_b32_e32 v189, 0
	s_and_b64 s[0:1], s[0:1], s[72:73]
	s_and_b64 s[0:1], s[0:1], s[66:67]
	s_and_b64 exec, s[96:97], s[0:1]
	s_cbranch_execz .Lglu_skip15
	v_mad_i64_i32 v[192:193], s[72:73], v194, s92, v[18:19]
	global_load_dword v65, v[192:193], off
	global_load_dword v73, v[192:193], off offset:4
	global_load_dword v187, v[192:193], off offset:512
	global_load_dword v189, v[192:193], off offset:516
.Lglu_skip15:
	s_mov_b64 exec, s[96:97]
	s_waitcnt vmcnt(0)
	v_lshlrev_b32_e32 v10, 16, v11
	v_and_b32_e32 v11, 0xffff0000, v11
	v_lshlrev_b32_e32 v12, 16, v13
	v_and_b32_e32 v13, 0xffff0000, v13
	v_lshlrev_b32_e32 v109, 16, v110
	v_and_b32_e32 v110, 0xffff0000, v110
	v_lshlrev_b32_e32 v111, 16, v112
	v_and_b32_e32 v112, 0xffff0000, v112
	v_lshlrev_b32_e32 v8, 16, v9
	v_and_b32_e32 v9, 0xffff0000, v9
	v_lshlrev_b32_e32 v16, 16, v17
	v_and_b32_e32 v17, 0xffff0000, v17
	v_lshlrev_b32_e32 v114, 16, v115
	v_and_b32_e32 v115, 0xffff0000, v115
	v_lshlrev_b32_e32 v116, 16, v117
	v_and_b32_e32 v117, 0xffff0000, v117
	v_lshlrev_b32_e32 v20, 16, v21
	v_and_b32_e32 v21, 0xffff0000, v21
	v_lshlrev_b32_e32 v22, 16, v23
	v_and_b32_e32 v23, 0xffff0000, v23
	v_lshlrev_b32_e32 v119, 16, v120
	v_and_b32_e32 v120, 0xffff0000, v120
	v_lshlrev_b32_e32 v121, 16, v125
	v_and_b32_e32 v125, 0xffff0000, v125
	v_lshlrev_b32_e32 v14, 16, v15
	v_and_b32_e32 v15, 0xffff0000, v15
	v_lshlrev_b32_e32 v26, 16, v27
	v_and_b32_e32 v27, 0xffff0000, v27
	v_lshlrev_b32_e32 v127, 16, v128
	v_and_b32_e32 v128, 0xffff0000, v128
	v_lshlrev_b32_e32 v129, 16, v130
	v_and_b32_e32 v130, 0xffff0000, v130
	v_lshlrev_b32_e32 v28, 16, v29
	v_and_b32_e32 v29, 0xffff0000, v29
	v_lshlrev_b32_e32 v30, 16, v31
	v_and_b32_e32 v31, 0xffff0000, v31
	v_lshlrev_b32_e32 v132, 16, v133
	v_and_b32_e32 v133, 0xffff0000, v133
	v_lshlrev_b32_e32 v134, 16, v135
	v_and_b32_e32 v135, 0xffff0000, v135
	v_lshlrev_b32_e32 v24, 16, v25
	v_and_b32_e32 v25, 0xffff0000, v25
	v_lshlrev_b32_e32 v34, 16, v35
	v_and_b32_e32 v35, 0xffff0000, v35
	v_lshlrev_b32_e32 v137, 16, v138
	v_and_b32_e32 v138, 0xffff0000, v138
	v_lshlrev_b32_e32 v139, 16, v140
	v_and_b32_e32 v140, 0xffff0000, v140
	v_lshlrev_b32_e32 v36, 16, v37
	v_and_b32_e32 v37, 0xffff0000, v37
	v_lshlrev_b32_e32 v38, 16, v39
	v_and_b32_e32 v39, 0xffff0000, v39
	v_lshlrev_b32_e32 v142, 16, v143
	v_and_b32_e32 v143, 0xffff0000, v143
	v_lshlrev_b32_e32 v144, 16, v145
	v_and_b32_e32 v145, 0xffff0000, v145
	v_lshlrev_b32_e32 v32, 16, v33
	v_and_b32_e32 v33, 0xffff0000, v33
	v_lshlrev_b32_e32 v42, 16, v43
	v_and_b32_e32 v43, 0xffff0000, v43
	v_lshlrev_b32_e32 v147, 16, v148
	v_and_b32_e32 v148, 0xffff0000, v148
	v_lshlrev_b32_e32 v149, 16, v150
	v_and_b32_e32 v150, 0xffff0000, v150
	v_lshlrev_b32_e32 v44, 16, v45
	v_and_b32_e32 v45, 0xffff0000, v45
	v_lshlrev_b32_e32 v46, 16, v47
	v_and_b32_e32 v47, 0xffff0000, v47
	v_lshlrev_b32_e32 v152, 16, v153
	v_and_b32_e32 v153, 0xffff0000, v153
	v_lshlrev_b32_e32 v154, 16, v155
	v_and_b32_e32 v155, 0xffff0000, v155
	v_lshlrev_b32_e32 v40, 16, v41
	v_and_b32_e32 v41, 0xffff0000, v41
	v_lshlrev_b32_e32 v50, 16, v51
	v_and_b32_e32 v51, 0xffff0000, v51
	v_lshlrev_b32_e32 v157, 16, v158
	v_and_b32_e32 v158, 0xffff0000, v158
	v_lshlrev_b32_e32 v159, 16, v160
	v_and_b32_e32 v160, 0xffff0000, v160
	v_lshlrev_b32_e32 v52, 16, v53
	v_and_b32_e32 v53, 0xffff0000, v53
	v_lshlrev_b32_e32 v54, 16, v55
	v_and_b32_e32 v55, 0xffff0000, v55
	v_lshlrev_b32_e32 v162, 16, v163
	v_and_b32_e32 v163, 0xffff0000, v163
	v_lshlrev_b32_e32 v164, 16, v165
	v_and_b32_e32 v165, 0xffff0000, v165
	v_lshlrev_b32_e32 v48, 16, v49
	v_and_b32_e32 v49, 0xffff0000, v49
	v_lshlrev_b32_e32 v58, 16, v59
	v_and_b32_e32 v59, 0xffff0000, v59
	v_lshlrev_b32_e32 v167, 16, v168
	v_and_b32_e32 v168, 0xffff0000, v168
	v_lshlrev_b32_e32 v169, 16, v170
	v_and_b32_e32 v170, 0xffff0000, v170
	v_lshlrev_b32_e32 v60, 16, v61
	v_and_b32_e32 v61, 0xffff0000, v61
	v_lshlrev_b32_e32 v62, 16, v63
	v_and_b32_e32 v63, 0xffff0000, v63
	v_lshlrev_b32_e32 v172, 16, v173
	v_and_b32_e32 v173, 0xffff0000, v173
	v_lshlrev_b32_e32 v174, 16, v175
	v_and_b32_e32 v175, 0xffff0000, v175
	v_lshlrev_b32_e32 v56, 16, v57
	v_and_b32_e32 v57, 0xffff0000, v57
	v_lshlrev_b32_e32 v66, 16, v67
	v_and_b32_e32 v67, 0xffff0000, v67
	v_lshlrev_b32_e32 v177, 16, v178
	v_and_b32_e32 v178, 0xffff0000, v178
	v_lshlrev_b32_e32 v179, 16, v180
	v_and_b32_e32 v180, 0xffff0000, v180
	v_lshlrev_b32_e32 v68, 16, v69
	v_and_b32_e32 v69, 0xffff0000, v69
	v_lshlrev_b32_e32 v70, 16, v71
	v_and_b32_e32 v71, 0xffff0000, v71
	v_lshlrev_b32_e32 v182, 16, v183
	v_and_b32_e32 v183, 0xffff0000, v183
	v_lshlrev_b32_e32 v184, 16, v185
	v_and_b32_e32 v185, 0xffff0000, v185
	v_lshlrev_b32_e32 v64, 16, v65
	v_and_b32_e32 v65, 0xffff0000, v65
	v_lshlrev_b32_e32 v72, 16, v73
	v_and_b32_e32 v73, 0xffff0000, v73
	v_lshlrev_b32_e32 v186, 16, v187
	v_and_b32_e32 v187, 0xffff0000, v187
	v_lshlrev_b32_e32 v188, 16, v189
	v_and_b32_e32 v189, 0xffff0000, v189
	s_or_b64 exec, exec, s[96:97]
	v_lshl_add_u32 v102, v102, 2, s69
	s_and_saveexec_b64 s[0:1], vcc
	s_cbranch_execnz .LBB0_540
